# plus: FoX vote c[key0-1] load prefetched at step top, wave-0 c-row load no longer waits behind its issue; gate cumsum partial-sum loop issues all loads before the adds
# speedup vs baseline: 1.0136x; 1.0136x over previous
; #define WSP(T, off) ((T*)wsoff(off))
; __global__ void __launch_bounds__(512, 2) fwd_kernel(Args args) {
;     ...
;                     const int h = wgi >> 4, seg = wgi & 15;
;                     const float* src = WSP(float, WS_LOGF) + (size_t)h * S;
;                     double part = 0.0;
;                     for (int i = tid; i < seg * 1024; i += 512) part += (double)src[i];
.LBB0_876:
	s_mov_b64 s[2:3], 0xa8
	s_ashr_i32 s20, s0, 4
	s_add_u32 s2, s74, s2
	s_addc_u32 s3, s75, s3
	s_load_dwordx2 s[4:5], s[2:3], 0x0
	s_lshl_b32 s1, s0, 10
	s_and_b32 s1, s1, 0x3c00
	s_mov_b64 s[22:23], 0x200000
	s_ashr_i32 s21, s20, 31
	v_cmp_gt_i32_e64 s[18:19], s1, v2
	v_mov_b64_e32 v[6:7], 0
	s_and_saveexec_b64 s[24:25], s[18:19]
	s_cbranch_execz .LBB0_880
	s_lshl_b64 s[2:3], s[20:21], 16
	s_add_u32 s2, s22, s2
	s_waitcnt lgkmcnt(0)
	v_lshl_add_u64 v[6:7], s[4:5], 0, v[4:5]
	s_addc_u32 s3, s23, s3
	v_lshl_add_u64 v[8:9], v[6:7], 0, s[2:3]
	v_mov_b64_e32 v[6:7], 0
	s_mov_b64 s[26:27], 0
	v_mov_b32_e32 v3, v2
	s_lshr_b32 s100, s1, 9
	s_mov_b64 s[2:3], 0x800
	s_cmp_le_u32 s100, 0
	s_cbranch_scc1 .Lcs_issued
	global_load_dword v64, v[8:9], off
	v_lshl_add_u64 v[8:9], v[8:9], 0, s[2:3]
	s_cmp_le_u32 s100, 1
	s_cbranch_scc1 .Lcs_issued
	global_load_dword v65, v[8:9], off
	v_lshl_add_u64 v[8:9], v[8:9], 0, s[2:3]
	s_cmp_le_u32 s100, 2
	s_cbranch_scc1 .Lcs_issued
	global_load_dword v66, v[8:9], off
	v_lshl_add_u64 v[8:9], v[8:9], 0, s[2:3]
	s_cmp_le_u32 s100, 3
	s_cbranch_scc1 .Lcs_issued
	global_load_dword v67, v[8:9], off
	v_lshl_add_u64 v[8:9], v[8:9], 0, s[2:3]
	s_cmp_le_u32 s100, 4
	s_cbranch_scc1 .Lcs_issued
	global_load_dword v68, v[8:9], off
	v_lshl_add_u64 v[8:9], v[8:9], 0, s[2:3]
	s_cmp_le_u32 s100, 5
	s_cbranch_scc1 .Lcs_issued
	global_load_dword v69, v[8:9], off
	v_lshl_add_u64 v[8:9], v[8:9], 0, s[2:3]
	s_cmp_le_u32 s100, 6
	s_cbranch_scc1 .Lcs_issued
	global_load_dword v70, v[8:9], off
	v_lshl_add_u64 v[8:9], v[8:9], 0, s[2:3]
	s_cmp_le_u32 s100, 7
	s_cbranch_scc1 .Lcs_issued
	global_load_dword v71, v[8:9], off
	v_lshl_add_u64 v[8:9], v[8:9], 0, s[2:3]
	s_cmp_le_u32 s100, 8
	s_cbranch_scc1 .Lcs_issued
	global_load_dword v72, v[8:9], off
	v_lshl_add_u64 v[8:9], v[8:9], 0, s[2:3]
	s_cmp_le_u32 s100, 9
	s_cbranch_scc1 .Lcs_issued
	global_load_dword v73, v[8:9], off
	v_lshl_add_u64 v[8:9], v[8:9], 0, s[2:3]
	s_cmp_le_u32 s100, 10
	s_cbranch_scc1 .Lcs_issued
	global_load_dword v74, v[8:9], off
	v_lshl_add_u64 v[8:9], v[8:9], 0, s[2:3]
	s_cmp_le_u32 s100, 11
	s_cbranch_scc1 .Lcs_issued
	global_load_dword v75, v[8:9], off
	v_lshl_add_u64 v[8:9], v[8:9], 0, s[2:3]
	s_cmp_le_u32 s100, 12
	s_cbranch_scc1 .Lcs_issued
	global_load_dword v76, v[8:9], off
	v_lshl_add_u64 v[8:9], v[8:9], 0, s[2:3]
	s_cmp_le_u32 s100, 13
	s_cbranch_scc1 .Lcs_issued
	global_load_dword v77, v[8:9], off
	v_lshl_add_u64 v[8:9], v[8:9], 0, s[2:3]
	s_cmp_le_u32 s100, 14
	s_cbranch_scc1 .Lcs_issued
	global_load_dword v78, v[8:9], off
	v_lshl_add_u64 v[8:9], v[8:9], 0, s[2:3]
	s_cmp_le_u32 s100, 15
	s_cbranch_scc1 .Lcs_issued
	global_load_dword v79, v[8:9], off
	v_lshl_add_u64 v[8:9], v[8:9], 0, s[2:3]
	s_cmp_le_u32 s100, 16
	s_cbranch_scc1 .Lcs_issued
	global_load_dword v80, v[8:9], off
	v_lshl_add_u64 v[8:9], v[8:9], 0, s[2:3]
	s_cmp_le_u32 s100, 17
	s_cbranch_scc1 .Lcs_issued
	global_load_dword v81, v[8:9], off
	v_lshl_add_u64 v[8:9], v[8:9], 0, s[2:3]
	s_cmp_le_u32 s100, 18
	s_cbranch_scc1 .Lcs_issued
	global_load_dword v82, v[8:9], off
	v_lshl_add_u64 v[8:9], v[8:9], 0, s[2:3]
	s_cmp_le_u32 s100, 19
	s_cbranch_scc1 .Lcs_issued
	global_load_dword v83, v[8:9], off
	v_lshl_add_u64 v[8:9], v[8:9], 0, s[2:3]
	s_cmp_le_u32 s100, 20
	s_cbranch_scc1 .Lcs_issued
	global_load_dword v84, v[8:9], off
	v_lshl_add_u64 v[8:9], v[8:9], 0, s[2:3]
	s_cmp_le_u32 s100, 21
	s_cbranch_scc1 .Lcs_issued
	global_load_dword v85, v[8:9], off
	v_lshl_add_u64 v[8:9], v[8:9], 0, s[2:3]
	s_cmp_le_u32 s100, 22
	s_cbranch_scc1 .Lcs_issued
	global_load_dword v86, v[8:9], off
	v_lshl_add_u64 v[8:9], v[8:9], 0, s[2:3]
	s_cmp_le_u32 s100, 23
	s_cbranch_scc1 .Lcs_issued
	global_load_dword v87, v[8:9], off
	v_lshl_add_u64 v[8:9], v[8:9], 0, s[2:3]
	s_cmp_le_u32 s100, 24
	s_cbranch_scc1 .Lcs_issued
	global_load_dword v88, v[8:9], off
	v_lshl_add_u64 v[8:9], v[8:9], 0, s[2:3]
	s_cmp_le_u32 s100, 25
	s_cbranch_scc1 .Lcs_issued
	global_load_dword v89, v[8:9], off
	v_lshl_add_u64 v[8:9], v[8:9], 0, s[2:3]
	s_cmp_le_u32 s100, 26
	s_cbranch_scc1 .Lcs_issued
	global_load_dword v90, v[8:9], off
	v_lshl_add_u64 v[8:9], v[8:9], 0, s[2:3]
	s_cmp_le_u32 s100, 27
	s_cbranch_scc1 .Lcs_issued
	global_load_dword v91, v[8:9], off
	v_lshl_add_u64 v[8:9], v[8:9], 0, s[2:3]
	s_cmp_le_u32 s100, 28
	s_cbranch_scc1 .Lcs_issued
	global_load_dword v92, v[8:9], off
	v_lshl_add_u64 v[8:9], v[8:9], 0, s[2:3]
	s_cmp_le_u32 s100, 29
	s_cbranch_scc1 .Lcs_issued
	global_load_dword v93, v[8:9], off
	v_lshl_add_u64 v[8:9], v[8:9], 0, s[2:3]
; __global__ void __launch_bounds__(512, 2) fwd_kernel(Args args) {
;     ...
;                     double part = 0.0;
;                     for (int i = tid; i < seg * 1024; i += 512) part += (double)src[i];
.Lcs_issued:
	s_waitcnt vmcnt(0)
	s_cmp_le_u32 s100, 0
	s_cbranch_scc1 .Lcs_summed
	v_cvt_f64_f32_e32 v[10:11], v64
	v_add_f64 v[6:7], v[6:7], v[10:11]
	s_cmp_le_u32 s100, 1
	s_cbranch_scc1 .Lcs_summed
	v_cvt_f64_f32_e32 v[10:11], v65
	v_add_f64 v[6:7], v[6:7], v[10:11]
	s_cmp_le_u32 s100, 2
	s_cbranch_scc1 .Lcs_summed
	v_cvt_f64_f32_e32 v[10:11], v66
	v_add_f64 v[6:7], v[6:7], v[10:11]
	s_cmp_le_u32 s100, 3
	s_cbranch_scc1 .Lcs_summed
	v_cvt_f64_f32_e32 v[10:11], v67
	v_add_f64 v[6:7], v[6:7], v[10:11]
	s_cmp_le_u32 s100, 4
	s_cbranch_scc1 .Lcs_summed
	v_cvt_f64_f32_e32 v[10:11], v68
	v_add_f64 v[6:7], v[6:7], v[10:11]
	s_cmp_le_u32 s100, 5
	s_cbranch_scc1 .Lcs_summed
	v_cvt_f64_f32_e32 v[10:11], v69
	v_add_f64 v[6:7], v[6:7], v[10:11]
	s_cmp_le_u32 s100, 6
	s_cbranch_scc1 .Lcs_summed
	v_cvt_f64_f32_e32 v[10:11], v70
	v_add_f64 v[6:7], v[6:7], v[10:11]
	s_cmp_le_u32 s100, 7
	s_cbranch_scc1 .Lcs_summed
	v_cvt_f64_f32_e32 v[10:11], v71
	v_add_f64 v[6:7], v[6:7], v[10:11]
	s_cmp_le_u32 s100, 8
	s_cbranch_scc1 .Lcs_summed
	v_cvt_f64_f32_e32 v[10:11], v72
	v_add_f64 v[6:7], v[6:7], v[10:11]
	s_cmp_le_u32 s100, 9
	s_cbranch_scc1 .Lcs_summed
	v_cvt_f64_f32_e32 v[10:11], v73
	v_add_f64 v[6:7], v[6:7], v[10:11]
	s_cmp_le_u32 s100, 10
	s_cbranch_scc1 .Lcs_summed
	v_cvt_f64_f32_e32 v[10:11], v74
	v_add_f64 v[6:7], v[6:7], v[10:11]
	s_cmp_le_u32 s100, 11
	s_cbranch_scc1 .Lcs_summed
	v_cvt_f64_f32_e32 v[10:11], v75
	v_add_f64 v[6:7], v[6:7], v[10:11]
	s_cmp_le_u32 s100, 12
	s_cbranch_scc1 .Lcs_summed
	v_cvt_f64_f32_e32 v[10:11], v76
	v_add_f64 v[6:7], v[6:7], v[10:11]
	s_cmp_le_u32 s100, 13
	s_cbranch_scc1 .Lcs_summed
	v_cvt_f64_f32_e32 v[10:11], v77
	v_add_f64 v[6:7], v[6:7], v[10:11]
	s_cmp_le_u32 s100, 14
	s_cbranch_scc1 .Lcs_summed
	v_cvt_f64_f32_e32 v[10:11], v78
	v_add_f64 v[6:7], v[6:7], v[10:11]
	s_cmp_le_u32 s100, 15
	s_cbranch_scc1 .Lcs_summed
	v_cvt_f64_f32_e32 v[10:11], v79
	v_add_f64 v[6:7], v[6:7], v[10:11]
	s_cmp_le_u32 s100, 16
	s_cbranch_scc1 .Lcs_summed
	v_cvt_f64_f32_e32 v[10:11], v80
	v_add_f64 v[6:7], v[6:7], v[10:11]
	s_cmp_le_u32 s100, 17
	s_cbranch_scc1 .Lcs_summed
	v_cvt_f64_f32_e32 v[10:11], v81
	v_add_f64 v[6:7], v[6:7], v[10:11]
	s_cmp_le_u32 s100, 18
	s_cbranch_scc1 .Lcs_summed
	v_cvt_f64_f32_e32 v[10:11], v82
	v_add_f64 v[6:7], v[6:7], v[10:11]
	s_cmp_le_u32 s100, 19
	s_cbranch_scc1 .Lcs_summed
	v_cvt_f64_f32_e32 v[10:11], v83
	v_add_f64 v[6:7], v[6:7], v[10:11]
	s_cmp_le_u32 s100, 20
	s_cbranch_scc1 .Lcs_summed
	v_cvt_f64_f32_e32 v[10:11], v84
	v_add_f64 v[6:7], v[6:7], v[10:11]
	s_cmp_le_u32 s100, 21
	s_cbranch_scc1 .Lcs_summed
	v_cvt_f64_f32_e32 v[10:11], v85
	v_add_f64 v[6:7], v[6:7], v[10:11]
	s_cmp_le_u32 s100, 22
	s_cbranch_scc1 .Lcs_summed
	v_cvt_f64_f32_e32 v[10:11], v86
	v_add_f64 v[6:7], v[6:7], v[10:11]
	s_cmp_le_u32 s100, 23
	s_cbranch_scc1 .Lcs_summed
	v_cvt_f64_f32_e32 v[10:11], v87
	v_add_f64 v[6:7], v[6:7], v[10:11]
	s_cmp_le_u32 s100, 24
	s_cbranch_scc1 .Lcs_summed
	v_cvt_f64_f32_e32 v[10:11], v88
	v_add_f64 v[6:7], v[6:7], v[10:11]
	s_cmp_le_u32 s100, 25
	s_cbranch_scc1 .Lcs_summed
	v_cvt_f64_f32_e32 v[10:11], v89
	v_add_f64 v[6:7], v[6:7], v[10:11]
	s_cmp_le_u32 s100, 26
	s_cbranch_scc1 .Lcs_summed
	v_cvt_f64_f32_e32 v[10:11], v90
	v_add_f64 v[6:7], v[6:7], v[10:11]
	s_cmp_le_u32 s100, 27
	s_cbranch_scc1 .Lcs_summed
	v_cvt_f64_f32_e32 v[10:11], v91
	v_add_f64 v[6:7], v[6:7], v[10:11]
	s_cmp_le_u32 s100, 28
	s_cbranch_scc1 .Lcs_summed
	v_cvt_f64_f32_e32 v[10:11], v92
	v_add_f64 v[6:7], v[6:7], v[10:11]
	s_cmp_le_u32 s100, 29
	s_cbranch_scc1 .Lcs_summed
	v_cvt_f64_f32_e32 v[10:11], v93
	v_add_f64 v[6:7], v[6:7], v[10:11]
.Lcs_summed:
	s_or_b64 exec, exec, s[26:27]
; __global__ void __launch_bounds__(512, 2) fwd_kernel(Args args) {
;     ...
;                     for (int o = 32; o >= 1; o >>= 1) part += __shfl_xor(part, o);
;                     const int e0 = seg * 1024 + 2 * tid; const double a = (double)src[e0], b = (double)src[e0 + 1];
;                     double incl = a + b;
; #pragma unroll
;                     for (int o = 1; o < 64; o <<= 1) { const double t = __shfl_up(incl, o); if (lane >= o) incl += t; }
;                     if (lane == 0) sc[wv] = part;
;                     if (lane == 63) sc[8 + wv] = incl;
.LBB0_880:
	s_or_b64 exec, exec, s[24:25]
	s_waitcnt lgkmcnt(0)
	s_add_u32 s18, s4, s22
	s_addc_u32 s19, s5, s23
	s_lshl_b64 s[4:5], s[20:21], 14
	s_lshl_b64 s[2:3], s[20:21], 16
	v_and_b32_e32 v3, 64, v223
	s_add_u32 s20, s18, s2
	v_add_u32_e32 v10, 64, v3
	v_xor_b32_e32 v8, 32, v223
	s_addc_u32 s21, s19, s3
	v_cmp_lt_i32_e64 s[18:19], v8, v10
	v_add_u32_e32 v18, -1, v223
	v_add_u32_e32 v20, -2, v223
	v_cndmask_b32_e64 v8, v223, v8, s[18:19]
	v_lshlrev_b32_e32 v9, 2, v8
	ds_bpermute_b32 v8, v9, v6
	ds_bpermute_b32 v9, v9, v7
	s_waitcnt lgkmcnt(0)
	v_add_f64 v[6:7], v[6:7], v[8:9]
	v_xor_b32_e32 v8, 16, v223
	v_cmp_lt_i32_e64 s[18:19], v8, v10
	s_nop 1
	v_cndmask_b32_e64 v8, v223, v8, s[18:19]
	v_lshlrev_b32_e32 v9, 2, v8
	ds_bpermute_b32 v8, v9, v6
	ds_bpermute_b32 v9, v9, v7
	s_waitcnt lgkmcnt(0)
	v_add_f64 v[6:7], v[6:7], v[8:9]
	v_xor_b32_e32 v8, 8, v223
	v_cmp_lt_i32_e64 s[18:19], v8, v10
	s_nop 1
	v_cndmask_b32_e64 v8, v223, v8, s[18:19]
	v_lshlrev_b32_e32 v9, 2, v8
	ds_bpermute_b32 v8, v9, v6
	ds_bpermute_b32 v9, v9, v7
	s_waitcnt lgkmcnt(0)
	v_add_f64 v[6:7], v[6:7], v[8:9]
	v_xor_b32_e32 v8, 4, v223
	v_cmp_lt_i32_e64 s[18:19], v8, v10
	s_nop 1
	v_cndmask_b32_e64 v8, v223, v8, s[18:19]
	v_lshlrev_b32_e32 v9, 2, v8
	ds_bpermute_b32 v8, v9, v6
	ds_bpermute_b32 v9, v9, v7
	s_waitcnt lgkmcnt(0)
	v_add_f64 v[6:7], v[6:7], v[8:9]
	v_xor_b32_e32 v8, 2, v223
	v_cmp_lt_i32_e64 s[18:19], v8, v10
	s_nop 1
	v_cndmask_b32_e64 v8, v223, v8, s[18:19]
	v_lshlrev_b32_e32 v9, 2, v8
	ds_bpermute_b32 v8, v9, v6
	ds_bpermute_b32 v9, v9, v7
	s_waitcnt lgkmcnt(0)
	v_add_f64 v[6:7], v[6:7], v[8:9]
	v_xor_b32_e32 v8, 1, v223
	v_cmp_lt_i32_e64 s[18:19], v8, v10
	v_add_u32_e32 v10, s1, v23
	v_ashrrev_i32_e32 v11, 31, v10
	v_lshl_add_u64 v[12:13], v[10:11], 2, s[20:21]
	global_load_dwordx2 v[14:15], v[12:13], off
	v_cndmask_b32_e64 v8, v223, v8, s[18:19]
	v_cmp_lt_i32_e64 s[18:19], v18, v3
	v_lshlrev_b32_e32 v9, 2, v8
	ds_bpermute_b32 v8, v9, v6
	v_cndmask_b32_e64 v18, v18, v223, s[18:19]
	v_lshlrev_b32_e32 v19, 2, v18
	v_cmp_lt_i32_e64 s[18:19], v20, v3
	ds_bpermute_b32 v9, v9, v7
	s_waitcnt vmcnt(0)
	v_cvt_f64_f32_e32 v[12:13], v14
	v_cvt_f64_f32_e32 v[14:15], v15
	v_add_f64 v[16:17], v[12:13], v[14:15]
	ds_bpermute_b32 v18, v19, v16
	ds_bpermute_b32 v19, v19, v17
	v_cndmask_b32_e64 v20, v20, v223, s[18:19]
	v_lshlrev_b32_e32 v21, 2, v20
	s_waitcnt lgkmcnt(0)
	v_add_f64 v[18:19], v[16:17], v[18:19]
	v_cndmask_b32_e64 v19, v19, v17, s[6:7]
	v_cndmask_b32_e64 v18, v18, v16, s[6:7]
	ds_bpermute_b32 v20, v21, v18
	ds_bpermute_b32 v21, v21, v19
	s_waitcnt lgkmcnt(0)
	v_add_f64 v[20:21], v[18:19], v[20:21]
	v_cndmask_b32_e64 v18, v20, v18, s[8:9]
	v_add_u32_e32 v20, -4, v223
	v_cmp_lt_i32_e64 s[18:19], v20, v3
	v_cndmask_b32_e64 v19, v21, v19, s[8:9]
	s_nop 0
	v_cndmask_b32_e64 v20, v20, v223, s[18:19]
	v_lshlrev_b32_e32 v21, 2, v20
	ds_bpermute_b32 v20, v21, v18
	ds_bpermute_b32 v21, v21, v19
	s_waitcnt lgkmcnt(0)
	v_add_f64 v[20:21], v[18:19], v[20:21]
	v_cndmask_b32_e64 v18, v20, v18, s[10:11]
	v_add_u32_e32 v20, -8, v223
	v_cmp_lt_i32_e64 s[18:19], v20, v3
	v_cndmask_b32_e64 v19, v21, v19, s[10:11]
	s_nop 0
	v_cndmask_b32_e64 v20, v20, v223, s[18:19]
	v_lshlrev_b32_e32 v21, 2, v20
	ds_bpermute_b32 v20, v21, v18
	ds_bpermute_b32 v21, v21, v19
	s_waitcnt lgkmcnt(0)
	v_add_f64 v[20:21], v[18:19], v[20:21]
	v_cndmask_b32_e64 v18, v20, v18, s[12:13]
	v_add_u32_e32 v20, -16, v223
	v_cmp_lt_i32_e64 s[18:19], v20, v3
	v_cndmask_b32_e64 v19, v21, v19, s[12:13]
	s_nop 0
	v_cndmask_b32_e64 v20, v20, v223, s[18:19]
	v_lshlrev_b32_e32 v21, 2, v20
	ds_bpermute_b32 v20, v21, v18
	ds_bpermute_b32 v21, v21, v19
	s_waitcnt lgkmcnt(0)
	v_add_f64 v[20:21], v[18:19], v[20:21]
	v_cndmask_b32_e64 v18, v20, v18, s[14:15]
	v_subrev_u32_e32 v20, 32, v223
	v_cmp_lt_i32_e64 s[18:19], v20, v3
	v_cndmask_b32_e64 v19, v21, v19, s[14:15]
	s_nop 0
	v_cndmask_b32_e64 v3, v20, v223, s[18:19]
	v_lshlrev_b32_e32 v3, 2, v3
	ds_bpermute_b32 v20, v3, v18
	ds_bpermute_b32 v21, v3, v19
	v_cmp_lt_i32_e64 s[18:19], 62, v0
	s_waitcnt lgkmcnt(0)
	v_add_f64 v[20:21], v[18:19], v[20:21]
	s_and_saveexec_b64 s[2:3], s[18:19]
	s_xor_b64 s[18:19], exec, s[2:3]
	ds_write_b64 v24, v[20:21] offset:64
	s_andn2_saveexec_b64 s[20:21], s[18:19]
	s_cbranch_execz .LBB0_886
	v_cmp_eq_u32_e64 s[18:19], 0, v0
	s_and_saveexec_b64 s[22:23], s[18:19]
	v_add_f64 v[6:7], v[6:7], v[8:9]
	ds_write_b64 v24, v[6:7]
	s_or_b64 exec, exec, s[22:23]

; #define LOADT(i, kreg, vreg, creg) do { const int k0_ = KEY0(i); kreg = *(const u32x4*)(A.K + (size_t)(k0_ + lane) * A.ldkv + wid * 8); vreg = *(const u32x4*)(A.V + (size_t)(k0_ + lane) * A.ldkv + wid * 8); \
;         if (MODE == M_FOX) { if (tid < 64) creg = A.cf[k0_ + tid] * LOG2E; } } while (0)
; template <int MODE>
; __device__ __forceinline__ void attn_unit(LAS unsigned char* lds, const AttnArgs& A, int qb) {
;     ...
;         { const int i = i0 + 0; if (i >= NT) break;
;         const int key0 = KEY0(i);
;         if (i + 3 < NT) LOADT(i + 3, k1, v1, c1);
.LBB0_964:
	s_add_i32 s55, s53, -5
	s_cmp_ge_u32 s55, s45
	s_mov_b64 s[10:11], -1
	s_cbranch_scc1 .LBB0_963
	s_add_i32 s0, s53, -2
	s_cmp_lt_u32 s0, s45
	s_cselect_b64 s[24:25], -1, 0
	s_cmp_ge_u32 s0, s45
	s_cbranch_scc1 .LBB0_969
	v_lshl_add_u64 v[2:3], v[168:169], 0, s[20:21]
	global_load_dwordx4 v[114:117], v[2:3], off
	v_lshl_add_u64 v[2:3], v[170:171], 0, s[20:21]
	global_load_dwordx4 v[118:121], v[2:3], off
	s_and_saveexec_b64 s[10:11], s[6:7]
	s_cbranch_execz .LBB0_968
	global_load_dword v157, v[172:173], off offset:256

; #define LAS __attribute__((address_space(3)))
; #define LOADT(i, kreg, vreg, creg) do { const int k0_ = KEY0(i); kreg = *(const u32x4*)(A.K + (size_t)(k0_ + lane) * A.ldkv + wid * 8); vreg = *(const u32x4*)(A.V + (size_t)(k0_ + lane) * A.ldkv + wid * 8); \
;         if (MODE == M_FOX) { if (tid < 64) creg = A.cf[k0_ + tid] * LOG2E; } } while (0)
; #define PVS(s, pk) do { const bf16x8 a0_ = *(const LAS bf16x8*)(vb + (s) * 32), a1_ = *(const LAS bf16x8*)(vb + 32 * VT_STRIDE + (s) * 32); \
;             o0 = __builtin_amdgcn_mfma_f32_32x32x16_bf16(a0_, pk, o0, 0, 0, 0); o1 = __builtin_amdgcn_mfma_f32_32x32x16_bf16(a1_, pk, o1, 0, 0, 0); } while (0)
; #define PVS(s, pk) do { const bf16x8 a0_ = *(const LAS bf16x8*)(vb + (s) * 32), a1_ = *(const LAS bf16x8*)(vb + 32 * VT_STRIDE + (s) * 32); \
;             o0 = __builtin_amdgcn_mfma_f32_32x32x16_bf16(a0_, pk, o0, 0, 0, 0); o1 = __builtin_amdgcn_mfma_f32_32x32x16_bf16(a1_, pk, o1, 0, 0, 0); } while (0)
; #define PVS(s, pk) do { const bf16x8 a0_ = *(const LAS bf16x8*)(vb + (s) * 32), a1_ = *(const LAS bf16x8*)(vb + 32 * VT_STRIDE + (s) * 32); \
;             o0 = __builtin_amdgcn_mfma_f32_32x32x16_bf16(a0_, pk, o0, 0, 0, 0); o1 = __builtin_amdgcn_mfma_f32_32x32x16_bf16(a1_, pk, o1, 0, 0, 0); } while (0)
; #define PVS(s, pk) do { const bf16x8 a0_ = *(const LAS bf16x8*)(vb + (s) * 32), a1_ = *(const LAS bf16x8*)(vb + 32 * VT_STRIDE + (s) * 32); \
;             o0 = __builtin_amdgcn_mfma_f32_32x32x16_bf16(a0_, pk, o0, 0, 0, 0); o1 = __builtin_amdgcn_mfma_f32_32x32x16_bf16(a1_, pk, o1, 0, 0, 0); } while (0)
; template <int MODE>
; __device__ __forceinline__ void attn_unit(LAS unsigned char* lds, const AttnArgs& A, int qb) {
;     ...
;         const int key0 = KEY0(i);
;         if (i + 3 < NT) LOADT(i + 3, k1, v1, c1);
;         LAS unsigned char* buf = lds + 0 * BUF_BYTES;
;         bool active;
;         if (MODE == M_XA) active = true;
;         else if (MODE == M_MOBA) active = (i < 4) ? (key0 <= w0 + 31) : (((wmask >> ((i - 4) >> 2)) & 1ull) != 0ull);
;         else active = key0 <= w0 + 31;
;     ...
;         if (prev_active) {
;             const LAS unsigned char* vb = lds + prevbuf + KB_BYTES + r32 * VT_STRIDE + hi * 16;
;     ...
;             PVS(0, pkP0); PVS(1, pkP1); PVS(2, pkP2); PVS(3, pkP3);
;     ...
;         }
.LBB0_969:
	s_sub_i32 s80, s52, 63
	s_cmp_lt_i32 s80, 1
	s_cbranch_scc1 .Lfox_cnskip0
	s_lshl_b64 s[100:101], s[80:81], 2
	s_add_u32 s100, s22, s100
	s_addc_u32 s101, s23, s101
	global_load_dword v228, v1, s[100:101] offset:-4
.Lfox_cnskip0:
	s_cmp_le_i32 s80, s48
	v_cndmask_b32_e64 v2, 0, 1, s[4:5]
	s_cselect_b64 s[26:27], -1, 0
	s_cmp_gt_i32 s80, s48
	s_mov_b64 s[28:29], -1
	v_cmp_ne_u32_e64 s[10:11], 1, v2
	s_cbranch_scc0 .LBB0_973
	v_mov_b64_e32 v[2:3], v[82:83]
	v_mov_b64_e32 v[18:19], v[66:67]
	s_and_b64 vcc, exec, s[10:11]
	v_mov_b64_e32 v[4:5], v[84:85]
	v_mov_b64_e32 v[6:7], v[86:87]
	v_mov_b64_e32 v[8:9], v[88:89]
	v_mov_b64_e32 v[10:11], v[90:91]
	v_mov_b64_e32 v[12:13], v[92:93]
	v_mov_b64_e32 v[14:15], v[94:95]
	v_mov_b64_e32 v[16:17], v[96:97]
	v_mov_b64_e32 v[20:21], v[68:69]
	v_mov_b64_e32 v[22:23], v[70:71]
	v_mov_b64_e32 v[24:25], v[72:73]
	v_mov_b64_e32 v[26:27], v[74:75]
	v_mov_b64_e32 v[28:29], v[76:77]
	v_mov_b64_e32 v[30:31], v[78:79]
	v_mov_b64_e32 v[32:33], v[80:81]
	s_cbranch_vccnz .LBB0_972
	v_add_u32_e32 v38, s2, v191
	ds_read_b128 v[18:21], v38 offset:8192
	ds_read_b128 v[34:37], v38 offset:12800
	s_waitcnt lgkmcnt(1)
	v_mfma_f32_32x32x16_bf16 v[2:17], v[18:21], v[150:153], v[82:97]
	s_waitcnt lgkmcnt(0)
	v_mfma_f32_32x32x16_bf16 v[18:33], v[34:37], v[150:153], v[66:81]
	ds_read_b128 v[34:37], v38 offset:8224
	s_waitcnt lgkmcnt(0)
	v_mfma_f32_32x32x16_bf16 v[2:17], v[34:37], v[142:145], v[2:17]
	ds_read_b128 v[34:37], v38 offset:12832
	s_waitcnt lgkmcnt(0)
	v_mfma_f32_32x32x16_bf16 v[18:33], v[34:37], v[142:145], v[18:33]
	ds_read_b128 v[34:37], v38 offset:8256
	s_waitcnt lgkmcnt(0)
	v_mfma_f32_32x32x16_bf16 v[2:17], v[34:37], v[146:149], v[2:17]
	ds_read_b128 v[34:37], v38 offset:12864
	s_waitcnt lgkmcnt(0)
	v_mfma_f32_32x32x16_bf16 v[18:33], v[34:37], v[146:149], v[18:33]
	ds_read_b128 v[34:37], v38 offset:8288
	s_waitcnt lgkmcnt(0)
	v_mfma_f32_32x32x16_bf16 v[2:17], v[34:37], v[138:141], v[2:17]
	ds_read_b128 v[34:37], v38 offset:12896
	s_waitcnt lgkmcnt(0)
	v_mfma_f32_32x32x16_bf16 v[18:33], v[34:37], v[138:141], v[18:33]

; template <int MODE>
; __device__ __forceinline__ void attn_unit(LAS unsigned char* lds, const AttnArgs& A, int qb) {
;     ...
;             if (MODE == M_SB) vote = __all(T < -151.0f) != 0;
;             else { const float cn = (key0 > 0) ? A.cf[key0 - 1] * LOG2E : 0.f; vote = __all(qb2 + cq2 - cn < m_run - 151.0f) != 0; }
.LBB0_985:
	s_cmp_lt_i32 s80, 1
	s_cbranch_scc1 .LBB0_987
	s_lshl_b64 s[0:1], s[80:81], 2
	s_add_u32 s0, s22, s0
	s_addc_u32 s1, s23, s1
	s_waitcnt vmcnt(0)
	v_mul_f32_e32 v34, 0x3fb8aa3b, v228
	s_branch .LBB0_988

; #define LAS __attribute__((address_space(3)))
; template <int MODE>
; __device__ __forceinline__ void attn_unit(LAS unsigned char* lds, const AttnArgs& A, int qb) {
;     ...
;             if (MODE == M_SB) vote = __all(T < -151.0f) != 0;
;             else { const float cn = (key0 > 0) ? A.cf[key0 - 1] * LOG2E : 0.f; vote = __all(qb2 + cq2 - cn < m_run - 151.0f) != 0; }
;             if (lane == 0) ((LAS unsigned*)(lds + VOTE_OFF))[(i & 1) * 8 + wid] = (active && vote) ? 1u : 0u;
.LBB0_988:
	s_waitcnt vmcnt(0)
	v_mul_f32_e32 v157, 0x3fb8aa3b, v157
	v_sub_f32_e32 v34, v190, v34
	v_add_f32_e32 v35, 0xc3170000, v193
	s_add_i32 s0, s51, -8
	s_mov_b64 s[10:11], exec
	v_cmp_lt_f32_e32 vcc, v34, v35
	s_and_b32 s0, s0, 8
	s_and_saveexec_b64 s[28:29], s[8:9]
	s_cbranch_execz .LBB0_990
	s_lshl_b32 s1, s0, 2
	s_add_i32 s1, s46, s1
	s_cmp_eq_u64 vcc, s[10:11]
	s_cselect_b64 s[2:3], -1, 0
	s_and_b64 s[2:3], s[26:27], s[2:3]
	v_cndmask_b32_e64 v34, 0, 1, s[2:3]
	v_mov_b32_e32 v35, s1
	ds_write_b32 v35, v34 offset:52992

; #define LOADT(i, kreg, vreg, creg) do { const int k0_ = KEY0(i); kreg = *(const u32x4*)(A.K + (size_t)(k0_ + lane) * A.ldkv + wid * 8); vreg = *(const u32x4*)(A.V + (size_t)(k0_ + lane) * A.ldkv + wid * 8); \
;         if (MODE == M_FOX) { if (tid < 64) creg = A.cf[k0_ + tid] * LOG2E; } } while (0)
; template <int MODE>
; __device__ __forceinline__ void attn_unit(LAS unsigned char* lds, const AttnArgs& A, int qb) {
;     ...
;         { const int i = i0 + 1; if (i >= NT) break;
;         const int key0 = KEY0(i);
;         if (i + 3 < NT) LOADT(i + 3, k2, v2, c2);
.LBB0_992:
	s_andn2_b64 vcc, exec, s[4:5]
	s_cbranch_vccnz .LBB0_1002
	s_cmp_ge_u32 s55, s44
	s_cbranch_scc1 .LBB0_997
	v_lshl_add_u64 v[34:35], v[162:163], 0, s[20:21]
	global_load_dwordx4 v[122:125], v[34:35], off
	v_lshl_add_u64 v[34:35], v[164:165], 0, s[20:21]
	global_load_dwordx4 v[126:129], v[34:35], off
	s_and_saveexec_b64 s[4:5], s[6:7]
	s_cbranch_execz .LBB0_996
	global_load_dword v177, v[172:173], off

; #define LAS __attribute__((address_space(3)))
; #define LOADT(i, kreg, vreg, creg) do { const int k0_ = KEY0(i); kreg = *(const u32x4*)(A.K + (size_t)(k0_ + lane) * A.ldkv + wid * 8); vreg = *(const u32x4*)(A.V + (size_t)(k0_ + lane) * A.ldkv + wid * 8); \
;         if (MODE == M_FOX) { if (tid < 64) creg = A.cf[k0_ + tid] * LOG2E; } } while (0)
; #define PVS(s, pk) do { const bf16x8 a0_ = *(const LAS bf16x8*)(vb + (s) * 32), a1_ = *(const LAS bf16x8*)(vb + 32 * VT_STRIDE + (s) * 32); \
;             o0 = __builtin_amdgcn_mfma_f32_32x32x16_bf16(a0_, pk, o0, 0, 0, 0); o1 = __builtin_amdgcn_mfma_f32_32x32x16_bf16(a1_, pk, o1, 0, 0, 0); } while (0)
; #define PVS(s, pk) do { const bf16x8 a0_ = *(const LAS bf16x8*)(vb + (s) * 32), a1_ = *(const LAS bf16x8*)(vb + 32 * VT_STRIDE + (s) * 32); \
;             o0 = __builtin_amdgcn_mfma_f32_32x32x16_bf16(a0_, pk, o0, 0, 0, 0); o1 = __builtin_amdgcn_mfma_f32_32x32x16_bf16(a1_, pk, o1, 0, 0, 0); } while (0)
; template <int MODE>
; __device__ __forceinline__ void attn_unit(LAS unsigned char* lds, const AttnArgs& A, int qb) {
;     ...
;         { const int i = i0 + 1; if (i >= NT) break;
;         const int key0 = KEY0(i);
;         if (i + 3 < NT) LOADT(i + 3, k2, v2, c2);
;         LAS unsigned char* buf = lds + 1 * BUF_BYTES;
;         bool active;
;         if (MODE == M_XA) active = true;
;         else if (MODE == M_MOBA) active = (i < 4) ? (key0 <= w0 + 31) : (((wmask >> ((i - 4) >> 2)) & 1ull) != 0ull);
;         else active = key0 <= w0 + 31;
;         if (active) {
;             f32x16 p0, p1;
; #pragma unroll
;             for (int r = 0; r < 16; ++r) { p0[r] = 0.f; p1[r] = 0.f; }
;             LAS unsigned char* kb = buf + kperm * 16 + hi * 1024;
; #pragma unroll
;             for (int d0 = 0; d0 < 4; ++d0) {
;                 const bf16x8 kf0 = *(const LAS bf16x8*)(kb + d0 * 2048), kf1 = *(const LAS bf16x8*)(kb + d0 * 2048 + 512);
;                 p0 = __builtin_amdgcn_mfma_f32_32x32x16_bf16(kf0, qr[d0], p0, 0, 0, 0);
;                 p1 = __builtin_amdgcn_mfma_f32_32x32x16_bf16(kf1, qr[d0], p1, 0, 0, 0);
;             }
;         if (prev_active) {
;             const LAS unsigned char* vb = lds + prevbuf + KB_BYTES + r32 * VT_STRIDE + hi * 16;
;     ...
;             PVS(0, pkP0); PVS(1, pkP1); PVS(2, pkP2); PVS(3, pkP3);
.LBB0_997:
	s_add_i32 s80, s52, 0xffffff81
	s_cmp_lt_i32 s80, 1
	s_cbranch_scc1 .Lfox_cnskip1
	s_lshl_b64 s[100:101], s[80:81], 2
	s_add_u32 s100, s22, s100
	s_addc_u32 s101, s23, s101
	global_load_dword v228, v1, s[100:101] offset:-4
.Lfox_cnskip1:
	s_cmp_le_i32 s80, s48
	s_cselect_b64 s[4:5], -1, 0
	s_cmp_gt_i32 s80, s48
	s_cbranch_scc1 .LBB0_1004
	v_add_u32_e32 v70, v186, v187
	ds_read_b128 v[34:37], v70 offset:17664
	ds_read_b128 v[50:53], v70 offset:18176
	ds_read_b128 v[66:69], v70 offset:19712
	s_andn2_b64 vcc, exec, s[26:27]
	s_waitcnt lgkmcnt(2)
	v_mfma_f32_32x32x16_bf16 v[34:49], v[34:37], v[98:101], 0
	s_waitcnt lgkmcnt(0)
	v_mfma_f32_32x32x16_bf16 v[34:49], v[66:69], v[102:105], v[34:49]
	ds_read_b128 v[66:69], v70 offset:20224
	v_mfma_f32_32x32x16_bf16 v[50:65], v[50:53], v[98:101], 0
	s_waitcnt lgkmcnt(0)
	v_mfma_f32_32x32x16_bf16 v[50:65], v[66:69], v[102:105], v[50:65]
	ds_read_b128 v[66:69], v70 offset:21760
	s_waitcnt lgkmcnt(0)
	v_mfma_f32_32x32x16_bf16 v[34:49], v[66:69], v[106:109], v[34:49]
	ds_read_b128 v[66:69], v70 offset:22272
	s_waitcnt lgkmcnt(0)
	v_mfma_f32_32x32x16_bf16 v[50:65], v[66:69], v[106:109], v[50:65]
	ds_read_b128 v[66:69], v70 offset:23808
	s_waitcnt lgkmcnt(0)
	v_mfma_f32_32x32x16_bf16 v[34:49], v[66:69], v[110:113], v[34:49]
	ds_read_b128 v[66:69], v70 offset:24320
	s_waitcnt lgkmcnt(0)
	v_mfma_f32_32x32x16_bf16 v[50:65], v[66:69], v[110:113], v[50:65]
	s_cbranch_vccnz .LBB0_1000
	ds_read_b128 v[66:69], v191 offset:8192
	s_waitcnt lgkmcnt(0)
	v_mfma_f32_32x32x16_bf16 v[2:17], v[66:69], v[150:153], v[2:17]
	ds_read_b128 v[66:69], v191 offset:12800
	s_waitcnt lgkmcnt(0)
	v_mfma_f32_32x32x16_bf16 v[18:33], v[66:69], v[150:153], v[18:33]
	ds_read_b128 v[66:69], v191 offset:8224
	s_waitcnt lgkmcnt(0)
	v_mfma_f32_32x32x16_bf16 v[2:17], v[66:69], v[142:145], v[2:17]
	ds_read_b128 v[66:69], v191 offset:12832
	s_waitcnt lgkmcnt(0)
	v_mfma_f32_32x32x16_bf16 v[18:33], v[66:69], v[142:145], v[18:33]
	ds_read_b128 v[66:69], v191 offset:8256
	s_waitcnt lgkmcnt(0)
	v_mfma_f32_32x32x16_bf16 v[2:17], v[66:69], v[146:149], v[2:17]
	ds_read_b128 v[66:69], v191 offset:12864
	s_waitcnt lgkmcnt(0)
	v_mfma_f32_32x32x16_bf16 v[18:33], v[66:69], v[146:149], v[18:33]
	ds_read_b128 v[66:69], v191 offset:8288
	s_waitcnt lgkmcnt(0)
	v_mfma_f32_32x32x16_bf16 v[2:17], v[66:69], v[138:141], v[2:17]
	ds_read_b128 v[66:69], v191 offset:12896
	s_waitcnt lgkmcnt(0)
	v_mfma_f32_32x32x16_bf16 v[18:33], v[66:69], v[138:141], v[18:33]

; #define LAS __attribute__((address_space(3)))
; template <int MODE>
; __device__ __forceinline__ void attn_unit(LAS unsigned char* lds, const AttnArgs& A, int qb) {
;     ...
;             if (MODE == M_SB) vote = __all(T < -151.0f) != 0;
;             else { const float cn = (key0 > 0) ? A.cf[key0 - 1] * LOG2E : 0.f; vote = __all(qb2 + cq2 - cn < m_run - 151.0f) != 0; }
;             if (lane == 0) ((LAS unsigned*)(lds + VOTE_OFF))[(i & 1) * 8 + wid] = (active && vote) ? 1u : 0u;
.LBB0_1013:
	s_lshl_b64 s[0:1], s[80:81], 2
	s_add_u32 s0, s22, s0
	s_addc_u32 s1, s23, s1
	s_waitcnt vmcnt(0)
	v_mul_f32_e32 v34, 0x3fb8aa3b, v228
.LBB0_1014:
	s_waitcnt vmcnt(0)
	v_mul_f32_e32 v177, 0x3fb8aa3b, v177
	v_sub_f32_e32 v34, v190, v34
	v_add_f32_e32 v35, 0xc3170000, v193
	s_mov_b64 s[26:27], exec
	v_cmp_lt_f32_e32 vcc, v34, v35
	s_and_b32 s0, s51, 8
	s_and_saveexec_b64 s[10:11], s[8:9]
	s_cbranch_execz .LBB0_1016
	s_lshl_b32 s1, s0, 2
	s_add_i32 s1, s46, s1
	s_cmp_eq_u64 vcc, s[26:27]
	s_cselect_b64 s[2:3], -1, 0
	s_and_b64 s[2:3], s[4:5], s[2:3]
	v_cndmask_b32_e64 v34, 0, 1, s[2:3]
	v_mov_b32_e32 v35, s1
	ds_write_b32 v35, v34 offset:52992

; #define LOADT(i, kreg, vreg, creg) do { const int k0_ = KEY0(i); kreg = *(const u32x4*)(A.K + (size_t)(k0_ + lane) * A.ldkv + wid * 8); vreg = *(const u32x4*)(A.V + (size_t)(k0_ + lane) * A.ldkv + wid * 8); \
;         if (MODE == M_FOX) { if (tid < 64) creg = A.cf[k0_ + tid] * LOG2E; } } while (0)
; template <int MODE>
; __device__ __forceinline__ void attn_unit(LAS unsigned char* lds, const AttnArgs& A, int qb) {
;     ...
;         { const int i = i0 + 2; if (i >= NT) break;
;         const int key0 = KEY0(i);
;         if (i + 3 < NT) LOADT(i + 3, k3, v3, c3);
.LBB0_1017:
	s_add_i32 s0, s53, -3
	s_cmp_ge_u32 s0, s45
	s_mov_b64 s[10:11], 0
	s_cbranch_scc1 .LBB0_1031
	s_cmp_ge_u32 s53, s45
	s_cbranch_scc1 .LBB0_1022
	v_lshl_add_u64 v[34:35], v[174:175], 0, s[20:21]
	global_load_dwordx4 v[130:133], v[34:35], off
	v_lshl_add_u64 v[34:35], v[166:167], 0, s[20:21]
	global_load_dwordx4 v[134:137], v[34:35], off
	s_and_saveexec_b64 s[10:11], s[6:7]
	s_cbranch_execz .LBB0_1021
	global_load_dword v178, v[172:173], off offset:-256

; #define LAS __attribute__((address_space(3)))
; #define LOADT(i, kreg, vreg, creg) do { const int k0_ = KEY0(i); kreg = *(const u32x4*)(A.K + (size_t)(k0_ + lane) * A.ldkv + wid * 8); vreg = *(const u32x4*)(A.V + (size_t)(k0_ + lane) * A.ldkv + wid * 8); \
;         if (MODE == M_FOX) { if (tid < 64) creg = A.cf[k0_ + tid] * LOG2E; } } while (0)
; #define PVS(s, pk) do { const bf16x8 a0_ = *(const LAS bf16x8*)(vb + (s) * 32), a1_ = *(const LAS bf16x8*)(vb + 32 * VT_STRIDE + (s) * 32); \
;             o0 = __builtin_amdgcn_mfma_f32_32x32x16_bf16(a0_, pk, o0, 0, 0, 0); o1 = __builtin_amdgcn_mfma_f32_32x32x16_bf16(a1_, pk, o1, 0, 0, 0); } while (0)
; #define PVS(s, pk) do { const bf16x8 a0_ = *(const LAS bf16x8*)(vb + (s) * 32), a1_ = *(const LAS bf16x8*)(vb + 32 * VT_STRIDE + (s) * 32); \
;             o0 = __builtin_amdgcn_mfma_f32_32x32x16_bf16(a0_, pk, o0, 0, 0, 0); o1 = __builtin_amdgcn_mfma_f32_32x32x16_bf16(a1_, pk, o1, 0, 0, 0); } while (0)
; #define PVS(s, pk) do { const bf16x8 a0_ = *(const LAS bf16x8*)(vb + (s) * 32), a1_ = *(const LAS bf16x8*)(vb + 32 * VT_STRIDE + (s) * 32); \
;             o0 = __builtin_amdgcn_mfma_f32_32x32x16_bf16(a0_, pk, o0, 0, 0, 0); o1 = __builtin_amdgcn_mfma_f32_32x32x16_bf16(a1_, pk, o1, 0, 0, 0); } while (0)
; #define PVS(s, pk) do { const bf16x8 a0_ = *(const LAS bf16x8*)(vb + (s) * 32), a1_ = *(const LAS bf16x8*)(vb + 32 * VT_STRIDE + (s) * 32); \
;             o0 = __builtin_amdgcn_mfma_f32_32x32x16_bf16(a0_, pk, o0, 0, 0, 0); o1 = __builtin_amdgcn_mfma_f32_32x32x16_bf16(a1_, pk, o1, 0, 0, 0); } while (0)
; template <int MODE>
; __device__ __forceinline__ void attn_unit(LAS unsigned char* lds, const AttnArgs& A, int qb) {
;     ...
;         { const int i = i0 + 2; if (i >= NT) break;
;         const int key0 = KEY0(i);
;         if (i + 3 < NT) LOADT(i + 3, k3, v3, c3);
;         LAS unsigned char* buf = lds + 2 * BUF_BYTES;
;         bool active;
;         if (MODE == M_XA) active = true;
;         else if (MODE == M_MOBA) active = (i < 4) ? (key0 <= w0 + 31) : (((wmask >> ((i - 4) >> 2)) & 1ull) != 0ull);
;         else active = key0 <= w0 + 31;
;     ...
;         if (prev_active) {
;             const LAS unsigned char* vb = lds + prevbuf + KB_BYTES + r32 * VT_STRIDE + hi * 16;
;     ...
;             PVS(0, pkP0); PVS(1, pkP1); PVS(2, pkP2); PVS(3, pkP3);
;     ...
;         }
.LBB0_1022:
	s_add_i32 s80, s52, 0xffffff41
	s_cmp_lt_i32 s80, 1
	s_cbranch_scc1 .Lfox_cnskip2
	s_lshl_b64 s[100:101], s[80:81], 2
	s_add_u32 s100, s22, s100
	s_addc_u32 s101, s23, s101
	global_load_dword v228, v1, s[100:101] offset:-4
.Lfox_cnskip2:
	s_cmp_le_i32 s80, s48
	v_cndmask_b32_e64 v34, 0, 1, s[4:5]
	s_cselect_b64 s[26:27], -1, 0
	s_cmp_gt_i32 s80, s48
	s_mov_b64 s[28:29], -1
	v_cmp_ne_u32_e64 s[10:11], 1, v34
	s_cbranch_scc0 .LBB0_1026
	v_mov_b64_e32 v[48:49], v[16:17]
	v_mov_b64_e32 v[64:65], v[32:33]
	s_and_b64 vcc, exec, s[10:11]
	v_mov_b64_e32 v[46:47], v[14:15]
	v_mov_b64_e32 v[44:45], v[12:13]
	v_mov_b64_e32 v[42:43], v[10:11]
	v_mov_b64_e32 v[40:41], v[8:9]
	v_mov_b64_e32 v[38:39], v[6:7]
	v_mov_b64_e32 v[36:37], v[4:5]
	v_mov_b64_e32 v[34:35], v[2:3]
	v_mov_b64_e32 v[62:63], v[30:31]
	v_mov_b64_e32 v[60:61], v[28:29]
	v_mov_b64_e32 v[58:59], v[26:27]
	v_mov_b64_e32 v[56:57], v[24:25]
	v_mov_b64_e32 v[54:55], v[22:23]
	v_mov_b64_e32 v[52:53], v[20:21]
	v_mov_b64_e32 v[50:51], v[18:19]
	s_cbranch_vccnz .LBB0_1025
	v_add_u32_e32 v70, s2, v191
	ds_read_b128 v[50:53], v70 offset:8192
	ds_read_b128 v[66:69], v70 offset:12800
	s_waitcnt lgkmcnt(1)
	v_mfma_f32_32x32x16_bf16 v[34:49], v[50:53], v[150:153], v[2:17]
	s_waitcnt lgkmcnt(0)
	v_mfma_f32_32x32x16_bf16 v[50:65], v[66:69], v[150:153], v[18:33]
	ds_read_b128 v[66:69], v70 offset:8224
	s_waitcnt lgkmcnt(0)
	v_mfma_f32_32x32x16_bf16 v[34:49], v[66:69], v[142:145], v[34:49]
	ds_read_b128 v[66:69], v70 offset:12832
	s_waitcnt lgkmcnt(0)
	v_mfma_f32_32x32x16_bf16 v[50:65], v[66:69], v[142:145], v[50:65]
	ds_read_b128 v[66:69], v70 offset:8256
	s_waitcnt lgkmcnt(0)
	v_mfma_f32_32x32x16_bf16 v[34:49], v[66:69], v[146:149], v[34:49]
	ds_read_b128 v[66:69], v70 offset:12864
	s_waitcnt lgkmcnt(0)
	v_mfma_f32_32x32x16_bf16 v[50:65], v[66:69], v[146:149], v[50:65]
	ds_read_b128 v[66:69], v70 offset:8288
	s_waitcnt lgkmcnt(0)
	v_mfma_f32_32x32x16_bf16 v[34:49], v[66:69], v[138:141], v[34:49]
	ds_read_b128 v[66:69], v70 offset:12896
	s_waitcnt lgkmcnt(0)
	v_mfma_f32_32x32x16_bf16 v[50:65], v[66:69], v[138:141], v[50:65]

; #define LAS __attribute__((address_space(3)))
; template <int MODE>
; __device__ __forceinline__ void attn_unit(LAS unsigned char* lds, const AttnArgs& A, int qb) {
;     ...
;             if (MODE == M_SB) vote = __all(T < -151.0f) != 0;
;             else { const float cn = (key0 > 0) ? A.cf[key0 - 1] * LOG2E : 0.f; vote = __all(qb2 + cq2 - cn < m_run - 151.0f) != 0; }
;             if (lane == 0) ((LAS unsigned*)(lds + VOTE_OFF))[(i & 1) * 8 + wid] = (active && vote) ? 1u : 0u;
.LBB0_1042:
	s_waitcnt vmcnt(0)
	v_mul_f32_e32 v178, 0x3fb8aa3b, v178
	v_sub_f32_e32 v34, v190, v34
	v_add_f32_e32 v35, 0xc3170000, v193
	s_mov_b64 s[10:11], exec
	v_cmp_lt_f32_e32 vcc, v34, v35
	s_and_saveexec_b64 s[4:5], s[8:9]
	s_cbranch_execz .LBB0_1044
	s_lshl_b32 s0, s42, 2
	s_add_i32 s2, s54, s0
	s_cmp_eq_u64 vcc, s[10:11]
	s_cselect_b64 s[0:1], -1, 0
	s_and_b64 s[0:1], s[26:27], s[0:1]
	v_cndmask_b32_e64 v34, 0, 1, s[0:1]
	v_mov_b32_e32 v35, s2
	ds_write_b32 v35, v34 offset:52992

; __device__ __forceinline__ void store4(bf16_t* p, f32x4 v) { u32x2 w; w.x = cvt_pk_bf16(v[0], v[1]); w.y = cvt_pk_bf16(v[2], v[3]); *(u32x2*)p = w; }
; __device__ __forceinline__ float rstd_of(const float* ssq, int row) { return rsqrtf(ssq[row] * (1.0f / 1024.0f) + 1e-6f); }
;     __device__ __forceinline__ void operator()(const f32x4 (&acc)[2][2][4][2], const Unit& u, int wr, int wc, int fr, int fq) const {
;         const int g0 = 252 * u.pm - 2 + 126 * wr + fr;
;         float rs[8];
; #pragma unroll
;         for (int q = 0; q < 8; ++q) { int r = g0 + 16 * q; r = r < 0 ? 0 : (r > SEQ - 1 ? SEQ - 1 : r); rs[q] = rstd_of(ssq, r); }
; #pragma unroll
;         for (int n = 0; n < 2; ++n) {
;             const int col = 128 * u.pn + 32 * wc + 8 * fq + 4 * n;
;             const f32x4 wg0 = *(const f32x4*)(cw + col), wg1 = *(const f32x4*)(cw + 5632 + col), wg2 = *(const f32x4*)(cw + 2 * 5632 + col), bg = *(const f32x4*)(cb + col);
;             const f32x4 wv0 = *(const f32x4*)(cw + 2816 + col), wv1 = *(const f32x4*)(cw + 5632 + 2816 + col), wv2 = *(const f32x4*)(cw + 2 * 5632 + 2816 + col), bv = *(const f32x4*)(cb + 2816 + col);
;             f32x4 pg = (f32x4){0.f, 0.f, 0.f, 0.f}, pv = (f32x4){0.f, 0.f, 0.f, 0.f};
; #pragma unroll
;             for (int q = 0; q < 8; ++q) {
;                 const f32x4 ug = acc[q >> 2][0][q & 3][n] * rs[q], uv = acc[q >> 2][1][q & 3][n] * rs[q];
;                 f32x4 res;
; #pragma unroll
;                 for (int j = 0; j < 4; ++j) {
;                     const float ga1 = dpp_ror1(ug[j]), gb1 = dpp_ror1(pg[j]), ga2 = dpp_ror2(ug[j]), gb2 = dpp_ror2(pg[j]);
;                     const float va1 = dpp_ror1(uv[j]), vb1 = dpp_ror1(pv[j]), va2 = dpp_ror2(uv[j]), vb2 = dpp_ror2(pv[j]);
;                     const float g1 = fr >= 1 ? ga1 : gb1, g2 = fr >= 2 ? ga2 : gb2, v1 = fr >= 1 ? va1 : vb1, v2 = fr >= 2 ? va2 : vb2;
;                     const float cgv = bg[j] + wg0[j] * g2 + wg1[j] * g1 + wg2[j] * ug[j];
;                     const float cvv = bv[j] + wv0[j] * v2 + wv1[j] * v1 + wv2[j] * uv[j];
;                     res[j] = cgv * __builtin_amdgcn_rcpf(1.0f + __builtin_amdgcn_exp2f(-1.44269504f * cgv)) * cvv;
;                 }
;                 pg = ug; pv = uv;
;                 const int row = g0 + 16 * q;
;                 if ((q > 0 || fr >= 2) && row < SEQ) store4(ACT + (size_t)row * 2816 + col, res);
.LBB0_2323:
	s_mulk_i32 s0, 0xfc
	v_add_u32_e32 v230, s0, v210
	s_movk_i32 s12, 0x3fff
	v_med3_i32 v234, v230, 0, s12
	v_lshlrev_b32_e32 v234, 2, v234
	global_load_dword v172, v234, s[28:29]
	v_add_u32_e32 v235, 16, v230
	v_med3_i32 v235, v235, 0, s12
	v_lshlrev_b32_e32 v235, 2, v235
	global_load_dword v173, v235, s[28:29]
	v_add_u32_e32 v236, 32, v230
	v_med3_i32 v236, v236, 0, s12
	v_lshlrev_b32_e32 v236, 2, v236
	global_load_dword v174, v236, s[28:29]
	v_add_u32_e32 v237, 48, v230
	v_med3_i32 v237, v237, 0, s12
	v_lshlrev_b32_e32 v237, 2, v237
	global_load_dword v175, v237, s[28:29]
	v_add_u32_e32 v238, 64, v230
	v_med3_i32 v238, v238, 0, s12
	v_lshlrev_b32_e32 v238, 2, v238
	global_load_dword v176, v238, s[28:29]
	v_add_u32_e32 v239, 80, v230
	v_med3_i32 v239, v239, 0, s12
	v_lshlrev_b32_e32 v239, 2, v239
	global_load_dword v177, v239, s[28:29]
	v_add_u32_e32 v240, 96, v230
	v_med3_i32 v240, v240, 0, s12
	v_lshlrev_b32_e32 v240, 2, v240
	global_load_dword v178, v240, s[28:29]
	v_add_u32_e32 v241, 112, v230
	v_med3_i32 v241, v241, 0, s12
	v_lshlrev_b32_e32 v241, 2, v241
	global_load_dword v179, v241, s[28:29]
	v_lshl_or_b32 v231, s4, 7, v211
	v_lshlrev_b32_e32 v232, 2, v231
	global_load_dwordx4 v[82:85], v232, s[30:31]
	global_load_dwordx4 v[86:89], v232, s[38:39]
	global_load_dwordx4 v[90:93], v232, s[40:41]
	global_load_dwordx4 v[94:97], v232, s[34:35]
	global_load_dwordx4 v[98:101], v232, s[42:43]
	global_load_dwordx4 v[102:105], v232, s[44:45]
	global_load_dwordx4 v[106:109], v232, s[46:47]
	global_load_dwordx4 v[110:113], v232, s[48:49]
	v_lshlrev_b32_e32 v231, 1, v231
	v_mad_i32_i24 v233, v230, s87, v231
	s_waitcnt vmcnt(8)
	v_fmamk_f32 v172, v172, 0x3a800000, v217
	v_fmamk_f32 v173, v173, 0x3a800000, v217
	v_fmamk_f32 v174, v174, 0x3a800000, v217
	v_fmamk_f32 v175, v175, 0x3a800000, v217
	v_fmamk_f32 v176, v176, 0x3a800000, v217
	v_fmamk_f32 v177, v177, 0x3a800000, v217
	v_fmamk_f32 v178, v178, 0x3a800000, v217
	v_fmamk_f32 v179, v179, 0x3a800000, v217
	v_rsq_f32_e32 v172, v172
	v_rsq_f32_e32 v173, v173
	v_rsq_f32_e32 v174, v174
	v_rsq_f32_e32 v175, v175
	v_rsq_f32_e32 v176, v176
	v_rsq_f32_e32 v177, v177
	v_rsq_f32_e32 v178, v178
	v_rsq_f32_e32 v179, v179
	s_waitcnt vmcnt(0)
	v_pk_mul_f32 v[158:159], v[158:159], v[172:173] op_sel_hi:[1,0]
	v_pk_mul_f32 v[160:161], v[160:161], v[172:173] op_sel_hi:[1,0]
	v_pk_mul_f32 v[154:155], v[154:155], v[172:173] op_sel_hi:[1,0]
	v_pk_mul_f32 v[156:157], v[156:157], v[172:173] op_sel_hi:[1,0]
	v_mov_b32_e32 v180, v94
	v_mov_b32_e32 v181, v95
	v_mov_b32_e32 v182, v96
	v_mov_b32_e32 v183, v97
	v_mov_b32_e32 v184, v110
	v_mov_b32_e32 v185, v111
	v_mov_b32_e32 v186, v112
	v_mov_b32_e32 v187, v113
	v_fmac_f32_dpp v180, v158, v82 row_shr:2 row_mask:0xf bank_mask:0xf
	v_fmac_f32_dpp v181, v159, v83 row_shr:2 row_mask:0xf bank_mask:0xf
	v_fmac_f32_dpp v182, v160, v84 row_shr:2 row_mask:0xf bank_mask:0xf
	v_fmac_f32_dpp v183, v161, v85 row_shr:2 row_mask:0xf bank_mask:0xf
	v_fmac_f32_dpp v184, v154, v98 row_shr:2 row_mask:0xf bank_mask:0xf
	v_fmac_f32_dpp v185, v155, v99 row_shr:2 row_mask:0xf bank_mask:0xf
	v_fmac_f32_dpp v186, v156, v100 row_shr:2 row_mask:0xf bank_mask:0xf
	v_fmac_f32_dpp v187, v157, v101 row_shr:2 row_mask:0xf bank_mask:0xf
	v_fmac_f32_dpp v180, v158, v86 row_shr:1 row_mask:0xf bank_mask:0xf
	v_fmac_f32_dpp v181, v159, v87 row_shr:1 row_mask:0xf bank_mask:0xf
	v_fmac_f32_dpp v182, v160, v88 row_shr:1 row_mask:0xf bank_mask:0xf
	v_fmac_f32_dpp v183, v161, v89 row_shr:1 row_mask:0xf bank_mask:0xf
	v_fmac_f32_dpp v184, v154, v102 row_shr:1 row_mask:0xf bank_mask:0xf
	v_fmac_f32_dpp v185, v155, v103 row_shr:1 row_mask:0xf bank_mask:0xf
	v_fmac_f32_dpp v186, v156, v104 row_shr:1 row_mask:0xf bank_mask:0xf
	v_fmac_f32_dpp v187, v157, v105 row_shr:1 row_mask:0xf bank_mask:0xf
	v_pk_fma_f32 v[180:181], v[158:159], v[90:91], v[180:181]
	v_pk_fma_f32 v[182:183], v[160:161], v[92:93], v[182:183]
	v_pk_fma_f32 v[184:185], v[154:155], v[106:107], v[184:185]
	v_pk_fma_f32 v[186:187], v[156:157], v[108:109], v[186:187]
	v_mul_f32_e32 v188, 0xbfb8aa3b, v180
	v_mul_f32_e32 v189, 0xbfb8aa3b, v181
	v_mul_f32_e32 v190, 0xbfb8aa3b, v182
	v_mul_f32_e32 v191, 0xbfb8aa3b, v183
	v_exp_f32_e32 v188, v188
	v_exp_f32_e32 v189, v189
	v_exp_f32_e32 v190, v190
	v_exp_f32_e32 v191, v191
	v_add_f32_e32 v188, 1.0, v188
	v_add_f32_e32 v189, 1.0, v189
	v_add_f32_e32 v190, 1.0, v190
	v_add_f32_e32 v191, 1.0, v191
	v_rcp_f32_e32 v188, v188
	v_rcp_f32_e32 v189, v189
	v_rcp_f32_e32 v190, v190
	v_rcp_f32_e32 v191, v191
	v_cmp_gt_i32_e32 vcc, 0x4000, v230
	v_pk_mul_f32 v[188:189], v[180:181], v[188:189]
	v_pk_mul_f32 v[190:191], v[182:183], v[190:191]
	v_pk_mul_f32 v[188:189], v[184:185], v[188:189]
	v_pk_mul_f32 v[190:191], v[186:187], v[190:191]
	s_and_b64 vcc, vcc, s[8:9]
	v_cvt_pk_bf16_f32 v206, v188, v189
	v_cvt_pk_bf16_f32 v207, v190, v191
	s_and_saveexec_b64 s[4:5], vcc
	s_cbranch_execz .Lupepi_skip0
	global_store_dwordx2 v233, v[206:207], s[26:27]
; __device__ __forceinline__ void store4(bf16_t* p, f32x4 v) { u32x2 w; w.x = cvt_pk_bf16(v[0], v[1]); w.y = cvt_pk_bf16(v[2], v[3]); *(u32x2*)p = w; }
; __device__ __forceinline__ float dpp_ror1(float x) { float r; asm volatile("s_nop 1\n\tv_mov_b32_dpp %0, %1 row_ror:1 row_mask:0xf bank_mask:0xf" : "=v"(r) : "v"(x)); return r; }
; __device__ __forceinline__ float dpp_ror2(float x) { float r; asm volatile("s_nop 1\n\tv_mov_b32_dpp %0, %1 row_ror:2 row_mask:0xf bank_mask:0xf" : "=v"(r) : "v"(x)); return r; }
;     __device__ __forceinline__ void operator()(const f32x4 (&acc)[2][2][4][2], const Unit& u, int wr, int wc, int fr, int fq) const {
;     ...
;             for (int q = 0; q < 8; ++q) {
;                 const f32x4 ug = acc[q >> 2][0][q & 3][n] * rs[q], uv = acc[q >> 2][1][q & 3][n] * rs[q];
;                 f32x4 res;
; #pragma unroll
;                 for (int j = 0; j < 4; ++j) {
;                     const float ga1 = dpp_ror1(ug[j]), gb1 = dpp_ror1(pg[j]), ga2 = dpp_ror2(ug[j]), gb2 = dpp_ror2(pg[j]);
;                     const float va1 = dpp_ror1(uv[j]), vb1 = dpp_ror1(pv[j]), va2 = dpp_ror2(uv[j]), vb2 = dpp_ror2(pv[j]);
;                     const float g1 = fr >= 1 ? ga1 : gb1, g2 = fr >= 2 ? ga2 : gb2, v1 = fr >= 1 ? va1 : vb1, v2 = fr >= 2 ? va2 : vb2;
;                     const float cgv = bg[j] + wg0[j] * g2 + wg1[j] * g1 + wg2[j] * ug[j];
;                     const float cvv = bv[j] + wv0[j] * v2 + wv1[j] * v1 + wv2[j] * uv[j];
;                     res[j] = cgv * __builtin_amdgcn_rcpf(1.0f + __builtin_amdgcn_exp2f(-1.44269504f * cgv)) * cvv;
;                 }
;                 pg = ug; pv = uv;
;                 const int row = g0 + 16 * q;
;                 if ((q > 0 || fr >= 2) && row < SEQ) store4(ACT + (size_t)row * 2816 + col, res);
.Lupepi_skip0:
	s_or_b64 exec, exec, s[4:5]
	v_pk_mul_f32 v[150:151], v[150:151], v[172:173] op_sel:[0,1] op_sel_hi:[1,1]
	v_pk_mul_f32 v[152:153], v[152:153], v[172:173] op_sel:[0,1] op_sel_hi:[1,1]
	v_pk_mul_f32 v[146:147], v[146:147], v[172:173] op_sel:[0,1] op_sel_hi:[1,1]
	v_pk_mul_f32 v[148:149], v[148:149], v[172:173] op_sel:[0,1] op_sel_hi:[1,1]
	v_mov_b32_e32 v180, v94
	v_mov_b32_e32 v181, v95
	v_mov_b32_e32 v182, v96
	v_mov_b32_e32 v183, v97
	v_mov_b32_e32 v184, v110
	v_mov_b32_e32 v185, v111
	v_mov_b32_e32 v186, v112
	v_mov_b32_e32 v187, v113
	v_fmac_f32_dpp v180, v150, v82 row_shr:2 row_mask:0xf bank_mask:0xf
	v_fmac_f32_dpp v181, v151, v83 row_shr:2 row_mask:0xf bank_mask:0xf
	v_fmac_f32_dpp v182, v152, v84 row_shr:2 row_mask:0xf bank_mask:0xf
	v_fmac_f32_dpp v183, v153, v85 row_shr:2 row_mask:0xf bank_mask:0xf
	v_fmac_f32_dpp v184, v146, v98 row_shr:2 row_mask:0xf bank_mask:0xf
	v_fmac_f32_dpp v185, v147, v99 row_shr:2 row_mask:0xf bank_mask:0xf
	v_fmac_f32_dpp v186, v148, v100 row_shr:2 row_mask:0xf bank_mask:0xf
	v_fmac_f32_dpp v187, v149, v101 row_shr:2 row_mask:0xf bank_mask:0xf
	v_fmac_f32_dpp v180, v158, v82 row_shl:14 row_mask:0xf bank_mask:0xf
	v_fmac_f32_dpp v181, v159, v83 row_shl:14 row_mask:0xf bank_mask:0xf
	v_fmac_f32_dpp v182, v160, v84 row_shl:14 row_mask:0xf bank_mask:0xf
	v_fmac_f32_dpp v183, v161, v85 row_shl:14 row_mask:0xf bank_mask:0xf
	v_fmac_f32_dpp v184, v154, v98 row_shl:14 row_mask:0xf bank_mask:0xf
	v_fmac_f32_dpp v185, v155, v99 row_shl:14 row_mask:0xf bank_mask:0xf
	v_fmac_f32_dpp v186, v156, v100 row_shl:14 row_mask:0xf bank_mask:0xf
	v_fmac_f32_dpp v187, v157, v101 row_shl:14 row_mask:0xf bank_mask:0xf
	v_fmac_f32_dpp v180, v150, v86 row_shr:1 row_mask:0xf bank_mask:0xf
	v_fmac_f32_dpp v181, v151, v87 row_shr:1 row_mask:0xf bank_mask:0xf
	v_fmac_f32_dpp v182, v152, v88 row_shr:1 row_mask:0xf bank_mask:0xf
	v_fmac_f32_dpp v183, v153, v89 row_shr:1 row_mask:0xf bank_mask:0xf
	v_fmac_f32_dpp v184, v146, v102 row_shr:1 row_mask:0xf bank_mask:0xf
	v_fmac_f32_dpp v185, v147, v103 row_shr:1 row_mask:0xf bank_mask:0xf
	v_fmac_f32_dpp v186, v148, v104 row_shr:1 row_mask:0xf bank_mask:0xf
	v_fmac_f32_dpp v187, v149, v105 row_shr:1 row_mask:0xf bank_mask:0xf
	v_fmac_f32_dpp v180, v158, v86 row_shl:15 row_mask:0xf bank_mask:0xf
	v_fmac_f32_dpp v181, v159, v87 row_shl:15 row_mask:0xf bank_mask:0xf
	v_fmac_f32_dpp v182, v160, v88 row_shl:15 row_mask:0xf bank_mask:0xf
	v_fmac_f32_dpp v183, v161, v89 row_shl:15 row_mask:0xf bank_mask:0xf
	v_fmac_f32_dpp v184, v154, v102 row_shl:15 row_mask:0xf bank_mask:0xf
	v_fmac_f32_dpp v185, v155, v103 row_shl:15 row_mask:0xf bank_mask:0xf
	v_fmac_f32_dpp v186, v156, v104 row_shl:15 row_mask:0xf bank_mask:0xf
	v_fmac_f32_dpp v187, v157, v105 row_shl:15 row_mask:0xf bank_mask:0xf
	v_pk_fma_f32 v[180:181], v[150:151], v[90:91], v[180:181]
	v_pk_fma_f32 v[182:183], v[152:153], v[92:93], v[182:183]
	v_pk_fma_f32 v[184:185], v[146:147], v[106:107], v[184:185]
	v_pk_fma_f32 v[186:187], v[148:149], v[108:109], v[186:187]
	v_mul_f32_e32 v188, 0xbfb8aa3b, v180
	v_mul_f32_e32 v189, 0xbfb8aa3b, v181
	v_mul_f32_e32 v190, 0xbfb8aa3b, v182
	v_mul_f32_e32 v191, 0xbfb8aa3b, v183
	v_exp_f32_e32 v188, v188
	v_exp_f32_e32 v189, v189
	v_exp_f32_e32 v190, v190
	v_exp_f32_e32 v191, v191
	v_add_f32_e32 v188, 1.0, v188
	v_add_f32_e32 v189, 1.0, v189
	v_add_f32_e32 v190, 1.0, v190
	v_add_f32_e32 v191, 1.0, v191
	v_rcp_f32_e32 v188, v188
	v_rcp_f32_e32 v189, v189
	v_rcp_f32_e32 v190, v190
	v_rcp_f32_e32 v191, v191
	v_cmp_gt_i32_e32 vcc, 0x3ff0, v230
	v_pk_mul_f32 v[188:189], v[180:181], v[188:189]
	v_pk_mul_f32 v[190:191], v[182:183], v[190:191]
	v_pk_mul_f32 v[188:189], v[184:185], v[188:189]
	v_pk_mul_f32 v[190:191], v[186:187], v[190:191]
	v_add_u32_e32 v234, 0x16000, v233
	v_cvt_pk_bf16_f32 v208, v188, v189
	v_cvt_pk_bf16_f32 v209, v190, v191
	s_and_saveexec_b64 s[4:5], vcc
	s_cbranch_execz .Lupepi_skip1
	global_store_dwordx2 v234, v[208:209], s[26:27]
.Lupepi_skip1:
	s_or_b64 exec, exec, s[4:5]
	v_pk_mul_f32 v[142:143], v[142:143], v[174:175] op_sel_hi:[1,0]
	v_pk_mul_f32 v[144:145], v[144:145], v[174:175] op_sel_hi:[1,0]
	v_pk_mul_f32 v[138:139], v[138:139], v[174:175] op_sel_hi:[1,0]
	v_pk_mul_f32 v[140:141], v[140:141], v[174:175] op_sel_hi:[1,0]
	v_mov_b32_e32 v180, v94
	v_mov_b32_e32 v181, v95
	v_mov_b32_e32 v182, v96
	v_mov_b32_e32 v183, v97
	v_mov_b32_e32 v184, v110
	v_mov_b32_e32 v185, v111
	v_mov_b32_e32 v186, v112
	v_mov_b32_e32 v187, v113
	v_fmac_f32_dpp v180, v142, v82 row_shr:2 row_mask:0xf bank_mask:0xf
	v_fmac_f32_dpp v181, v143, v83 row_shr:2 row_mask:0xf bank_mask:0xf
	v_fmac_f32_dpp v182, v144, v84 row_shr:2 row_mask:0xf bank_mask:0xf
	v_fmac_f32_dpp v183, v145, v85 row_shr:2 row_mask:0xf bank_mask:0xf
	v_fmac_f32_dpp v184, v138, v98 row_shr:2 row_mask:0xf bank_mask:0xf
	v_fmac_f32_dpp v185, v139, v99 row_shr:2 row_mask:0xf bank_mask:0xf
	v_fmac_f32_dpp v186, v140, v100 row_shr:2 row_mask:0xf bank_mask:0xf
	v_fmac_f32_dpp v187, v141, v101 row_shr:2 row_mask:0xf bank_mask:0xf
	v_fmac_f32_dpp v180, v150, v82 row_shl:14 row_mask:0xf bank_mask:0xf
	v_fmac_f32_dpp v181, v151, v83 row_shl:14 row_mask:0xf bank_mask:0xf
	v_fmac_f32_dpp v182, v152, v84 row_shl:14 row_mask:0xf bank_mask:0xf
	v_fmac_f32_dpp v183, v153, v85 row_shl:14 row_mask:0xf bank_mask:0xf
	v_fmac_f32_dpp v184, v146, v98 row_shl:14 row_mask:0xf bank_mask:0xf
	v_fmac_f32_dpp v185, v147, v99 row_shl:14 row_mask:0xf bank_mask:0xf
	v_fmac_f32_dpp v186, v148, v100 row_shl:14 row_mask:0xf bank_mask:0xf
	v_fmac_f32_dpp v187, v149, v101 row_shl:14 row_mask:0xf bank_mask:0xf
	v_fmac_f32_dpp v180, v142, v86 row_shr:1 row_mask:0xf bank_mask:0xf
; __device__ __forceinline__ void store4(bf16_t* p, f32x4 v) { u32x2 w; w.x = cvt_pk_bf16(v[0], v[1]); w.y = cvt_pk_bf16(v[2], v[3]); *(u32x2*)p = w; }
; __device__ __forceinline__ float dpp_ror1(float x) { float r; asm volatile("s_nop 1\n\tv_mov_b32_dpp %0, %1 row_ror:1 row_mask:0xf bank_mask:0xf" : "=v"(r) : "v"(x)); return r; }
; __device__ __forceinline__ float dpp_ror2(float x) { float r; asm volatile("s_nop 1\n\tv_mov_b32_dpp %0, %1 row_ror:2 row_mask:0xf bank_mask:0xf" : "=v"(r) : "v"(x)); return r; }
;     __device__ __forceinline__ void operator()(const f32x4 (&acc)[2][2][4][2], const Unit& u, int wr, int wc, int fr, int fq) const {
;     ...
;             for (int q = 0; q < 8; ++q) {
;                 const f32x4 ug = acc[q >> 2][0][q & 3][n] * rs[q], uv = acc[q >> 2][1][q & 3][n] * rs[q];
;                 f32x4 res;
; #pragma unroll
;                 for (int j = 0; j < 4; ++j) {
;                     const float ga1 = dpp_ror1(ug[j]), gb1 = dpp_ror1(pg[j]), ga2 = dpp_ror2(ug[j]), gb2 = dpp_ror2(pg[j]);
;                     const float va1 = dpp_ror1(uv[j]), vb1 = dpp_ror1(pv[j]), va2 = dpp_ror2(uv[j]), vb2 = dpp_ror2(pv[j]);
;                     const float g1 = fr >= 1 ? ga1 : gb1, g2 = fr >= 2 ? ga2 : gb2, v1 = fr >= 1 ? va1 : vb1, v2 = fr >= 2 ? va2 : vb2;
;                     const float cgv = bg[j] + wg0[j] * g2 + wg1[j] * g1 + wg2[j] * ug[j];
;                     const float cvv = bv[j] + wv0[j] * v2 + wv1[j] * v1 + wv2[j] * uv[j];
;                     res[j] = cgv * __builtin_amdgcn_rcpf(1.0f + __builtin_amdgcn_exp2f(-1.44269504f * cgv)) * cvv;
;                 }
;                 pg = ug; pv = uv;
;                 const int row = g0 + 16 * q;
;                 if ((q > 0 || fr >= 2) && row < SEQ) store4(ACT + (size_t)row * 2816 + col, res);
	v_fmac_f32_dpp v181, v143, v87 row_shr:1 row_mask:0xf bank_mask:0xf
	v_fmac_f32_dpp v182, v144, v88 row_shr:1 row_mask:0xf bank_mask:0xf
	v_fmac_f32_dpp v183, v145, v89 row_shr:1 row_mask:0xf bank_mask:0xf
	v_fmac_f32_dpp v184, v138, v102 row_shr:1 row_mask:0xf bank_mask:0xf
	v_fmac_f32_dpp v185, v139, v103 row_shr:1 row_mask:0xf bank_mask:0xf
	v_fmac_f32_dpp v186, v140, v104 row_shr:1 row_mask:0xf bank_mask:0xf
	v_fmac_f32_dpp v187, v141, v105 row_shr:1 row_mask:0xf bank_mask:0xf
	v_fmac_f32_dpp v180, v150, v86 row_shl:15 row_mask:0xf bank_mask:0xf
	v_fmac_f32_dpp v181, v151, v87 row_shl:15 row_mask:0xf bank_mask:0xf
	v_fmac_f32_dpp v182, v152, v88 row_shl:15 row_mask:0xf bank_mask:0xf
	v_fmac_f32_dpp v183, v153, v89 row_shl:15 row_mask:0xf bank_mask:0xf
	v_fmac_f32_dpp v184, v146, v102 row_shl:15 row_mask:0xf bank_mask:0xf
	v_fmac_f32_dpp v185, v147, v103 row_shl:15 row_mask:0xf bank_mask:0xf
	v_fmac_f32_dpp v186, v148, v104 row_shl:15 row_mask:0xf bank_mask:0xf
	v_fmac_f32_dpp v187, v149, v105 row_shl:15 row_mask:0xf bank_mask:0xf
	v_pk_fma_f32 v[180:181], v[142:143], v[90:91], v[180:181]
	v_pk_fma_f32 v[182:183], v[144:145], v[92:93], v[182:183]
	v_pk_fma_f32 v[184:185], v[138:139], v[106:107], v[184:185]
	v_pk_fma_f32 v[186:187], v[140:141], v[108:109], v[186:187]
	v_mul_f32_e32 v188, 0xbfb8aa3b, v180
	v_mul_f32_e32 v189, 0xbfb8aa3b, v181
	v_mul_f32_e32 v190, 0xbfb8aa3b, v182
	v_mul_f32_e32 v191, 0xbfb8aa3b, v183
	v_exp_f32_e32 v188, v188
	v_exp_f32_e32 v189, v189
	v_exp_f32_e32 v190, v190
	v_exp_f32_e32 v191, v191
	v_add_f32_e32 v188, 1.0, v188
	v_add_f32_e32 v189, 1.0, v189
	v_add_f32_e32 v190, 1.0, v190
	v_add_f32_e32 v191, 1.0, v191
	v_rcp_f32_e32 v188, v188
	v_rcp_f32_e32 v189, v189
	v_rcp_f32_e32 v190, v190
	v_rcp_f32_e32 v191, v191
	v_cmp_gt_i32_e32 vcc, 0x3fe0, v230
	v_pk_mul_f32 v[188:189], v[180:181], v[188:189]
	v_pk_mul_f32 v[190:191], v[182:183], v[190:191]
	v_pk_mul_f32 v[188:189], v[184:185], v[188:189]
	v_pk_mul_f32 v[190:191], v[186:187], v[190:191]
	v_add_u32_e32 v234, 0x2c000, v233
	v_cvt_pk_bf16_f32 v206, v188, v189
	v_cvt_pk_bf16_f32 v207, v190, v191
	s_and_saveexec_b64 s[4:5], vcc
	s_cbranch_execz .Lupepi_skip2
	global_store_dwordx2 v234, v[206:207], s[26:27]
.Lupepi_skip2:
	s_or_b64 exec, exec, s[4:5]
	v_pk_mul_f32 v[134:135], v[134:135], v[174:175] op_sel:[0,1] op_sel_hi:[1,1]
	v_pk_mul_f32 v[136:137], v[136:137], v[174:175] op_sel:[0,1] op_sel_hi:[1,1]
	v_pk_mul_f32 v[130:131], v[130:131], v[174:175] op_sel:[0,1] op_sel_hi:[1,1]
	v_pk_mul_f32 v[132:133], v[132:133], v[174:175] op_sel:[0,1] op_sel_hi:[1,1]
	v_mov_b32_e32 v180, v94
	v_mov_b32_e32 v181, v95
	v_mov_b32_e32 v182, v96
	v_mov_b32_e32 v183, v97
	v_mov_b32_e32 v184, v110
	v_mov_b32_e32 v185, v111
	v_mov_b32_e32 v186, v112
	v_mov_b32_e32 v187, v113
	v_fmac_f32_dpp v180, v134, v82 row_shr:2 row_mask:0xf bank_mask:0xf
	v_fmac_f32_dpp v181, v135, v83 row_shr:2 row_mask:0xf bank_mask:0xf
	v_fmac_f32_dpp v182, v136, v84 row_shr:2 row_mask:0xf bank_mask:0xf
	v_fmac_f32_dpp v183, v137, v85 row_shr:2 row_mask:0xf bank_mask:0xf
	v_fmac_f32_dpp v184, v130, v98 row_shr:2 row_mask:0xf bank_mask:0xf
	v_fmac_f32_dpp v185, v131, v99 row_shr:2 row_mask:0xf bank_mask:0xf
	v_fmac_f32_dpp v186, v132, v100 row_shr:2 row_mask:0xf bank_mask:0xf
	v_fmac_f32_dpp v187, v133, v101 row_shr:2 row_mask:0xf bank_mask:0xf
	v_fmac_f32_dpp v180, v142, v82 row_shl:14 row_mask:0xf bank_mask:0xf
	v_fmac_f32_dpp v181, v143, v83 row_shl:14 row_mask:0xf bank_mask:0xf
	v_fmac_f32_dpp v182, v144, v84 row_shl:14 row_mask:0xf bank_mask:0xf
	v_fmac_f32_dpp v183, v145, v85 row_shl:14 row_mask:0xf bank_mask:0xf
	v_fmac_f32_dpp v184, v138, v98 row_shl:14 row_mask:0xf bank_mask:0xf
	v_fmac_f32_dpp v185, v139, v99 row_shl:14 row_mask:0xf bank_mask:0xf
	v_fmac_f32_dpp v186, v140, v100 row_shl:14 row_mask:0xf bank_mask:0xf
	v_fmac_f32_dpp v187, v141, v101 row_shl:14 row_mask:0xf bank_mask:0xf
	v_fmac_f32_dpp v180, v134, v86 row_shr:1 row_mask:0xf bank_mask:0xf
	v_fmac_f32_dpp v181, v135, v87 row_shr:1 row_mask:0xf bank_mask:0xf
	v_fmac_f32_dpp v182, v136, v88 row_shr:1 row_mask:0xf bank_mask:0xf
	v_fmac_f32_dpp v183, v137, v89 row_shr:1 row_mask:0xf bank_mask:0xf
	v_fmac_f32_dpp v184, v130, v102 row_shr:1 row_mask:0xf bank_mask:0xf
	v_fmac_f32_dpp v185, v131, v103 row_shr:1 row_mask:0xf bank_mask:0xf
	v_fmac_f32_dpp v186, v132, v104 row_shr:1 row_mask:0xf bank_mask:0xf
	v_fmac_f32_dpp v187, v133, v105 row_shr:1 row_mask:0xf bank_mask:0xf
	v_fmac_f32_dpp v180, v142, v86 row_shl:15 row_mask:0xf bank_mask:0xf
	v_fmac_f32_dpp v181, v143, v87 row_shl:15 row_mask:0xf bank_mask:0xf
	v_fmac_f32_dpp v182, v144, v88 row_shl:15 row_mask:0xf bank_mask:0xf
	v_fmac_f32_dpp v183, v145, v89 row_shl:15 row_mask:0xf bank_mask:0xf
	v_fmac_f32_dpp v184, v138, v102 row_shl:15 row_mask:0xf bank_mask:0xf
	v_fmac_f32_dpp v185, v139, v103 row_shl:15 row_mask:0xf bank_mask:0xf
	v_fmac_f32_dpp v186, v140, v104 row_shl:15 row_mask:0xf bank_mask:0xf
	v_fmac_f32_dpp v187, v141, v105 row_shl:15 row_mask:0xf bank_mask:0xf
	v_pk_fma_f32 v[180:181], v[134:135], v[90:91], v[180:181]
	v_pk_fma_f32 v[182:183], v[136:137], v[92:93], v[182:183]
	v_pk_fma_f32 v[184:185], v[130:131], v[106:107], v[184:185]
	v_pk_fma_f32 v[186:187], v[132:133], v[108:109], v[186:187]
	v_mul_f32_e32 v188, 0xbfb8aa3b, v180
	v_mul_f32_e32 v189, 0xbfb8aa3b, v181
	v_mul_f32_e32 v190, 0xbfb8aa3b, v182
	v_mul_f32_e32 v191, 0xbfb8aa3b, v183
	v_exp_f32_e32 v188, v188
	v_exp_f32_e32 v189, v189
	v_exp_f32_e32 v190, v190
	v_exp_f32_e32 v191, v191
	v_add_f32_e32 v188, 1.0, v188
	v_add_f32_e32 v189, 1.0, v189
	v_add_f32_e32 v190, 1.0, v190
	v_add_f32_e32 v191, 1.0, v191
	v_rcp_f32_e32 v188, v188
	v_rcp_f32_e32 v189, v189
	v_rcp_f32_e32 v190, v190
	v_rcp_f32_e32 v191, v191
	v_cmp_gt_i32_e32 vcc, 0x3fd0, v230
	v_pk_mul_f32 v[188:189], v[180:181], v[188:189]
	v_pk_mul_f32 v[190:191], v[182:183], v[190:191]
	v_pk_mul_f32 v[188:189], v[184:185], v[188:189]
	v_pk_mul_f32 v[190:191], v[186:187], v[190:191]
	v_add_u32_e32 v234, 0x42000, v233
	v_cvt_pk_bf16_f32 v208, v188, v189
	v_cvt_pk_bf16_f32 v209, v190, v191
	s_and_saveexec_b64 s[4:5], vcc
	s_cbranch_execz .Lupepi_skip3
	global_store_dwordx2 v234, v[208:209], s[26:27]
; __device__ __forceinline__ void store4(bf16_t* p, f32x4 v) { u32x2 w; w.x = cvt_pk_bf16(v[0], v[1]); w.y = cvt_pk_bf16(v[2], v[3]); *(u32x2*)p = w; }
; __device__ __forceinline__ float dpp_ror1(float x) { float r; asm volatile("s_nop 1\n\tv_mov_b32_dpp %0, %1 row_ror:1 row_mask:0xf bank_mask:0xf" : "=v"(r) : "v"(x)); return r; }
; __device__ __forceinline__ float dpp_ror2(float x) { float r; asm volatile("s_nop 1\n\tv_mov_b32_dpp %0, %1 row_ror:2 row_mask:0xf bank_mask:0xf" : "=v"(r) : "v"(x)); return r; }
;     __device__ __forceinline__ void operator()(const f32x4 (&acc)[2][2][4][2], const Unit& u, int wr, int wc, int fr, int fq) const {
;     ...
;             for (int q = 0; q < 8; ++q) {
;                 const f32x4 ug = acc[q >> 2][0][q & 3][n] * rs[q], uv = acc[q >> 2][1][q & 3][n] * rs[q];
;                 f32x4 res;
; #pragma unroll
;                 for (int j = 0; j < 4; ++j) {
;                     const float ga1 = dpp_ror1(ug[j]), gb1 = dpp_ror1(pg[j]), ga2 = dpp_ror2(ug[j]), gb2 = dpp_ror2(pg[j]);
;                     const float va1 = dpp_ror1(uv[j]), vb1 = dpp_ror1(pv[j]), va2 = dpp_ror2(uv[j]), vb2 = dpp_ror2(pv[j]);
;                     const float g1 = fr >= 1 ? ga1 : gb1, g2 = fr >= 2 ? ga2 : gb2, v1 = fr >= 1 ? va1 : vb1, v2 = fr >= 2 ? va2 : vb2;
;                     const float cgv = bg[j] + wg0[j] * g2 + wg1[j] * g1 + wg2[j] * ug[j];
;                     const float cvv = bv[j] + wv0[j] * v2 + wv1[j] * v1 + wv2[j] * uv[j];
;                     res[j] = cgv * __builtin_amdgcn_rcpf(1.0f + __builtin_amdgcn_exp2f(-1.44269504f * cgv)) * cvv;
;                 }
;                 pg = ug; pv = uv;
;                 const int row = g0 + 16 * q;
;                 if ((q > 0 || fr >= 2) && row < SEQ) store4(ACT + (size_t)row * 2816 + col, res);
.Lupepi_skip3:
	s_or_b64 exec, exec, s[4:5]
	v_pk_mul_f32 v[126:127], v[126:127], v[176:177] op_sel_hi:[1,0]
	v_pk_mul_f32 v[128:129], v[128:129], v[176:177] op_sel_hi:[1,0]
	v_pk_mul_f32 v[122:123], v[122:123], v[176:177] op_sel_hi:[1,0]
	v_pk_mul_f32 v[124:125], v[124:125], v[176:177] op_sel_hi:[1,0]
	v_mov_b32_e32 v180, v94
	v_mov_b32_e32 v181, v95
	v_mov_b32_e32 v182, v96
	v_mov_b32_e32 v183, v97
	v_mov_b32_e32 v184, v110
	v_mov_b32_e32 v185, v111
	v_mov_b32_e32 v186, v112
	v_mov_b32_e32 v187, v113
	v_fmac_f32_dpp v180, v126, v82 row_shr:2 row_mask:0xf bank_mask:0xf
	v_fmac_f32_dpp v181, v127, v83 row_shr:2 row_mask:0xf bank_mask:0xf
	v_fmac_f32_dpp v182, v128, v84 row_shr:2 row_mask:0xf bank_mask:0xf
	v_fmac_f32_dpp v183, v129, v85 row_shr:2 row_mask:0xf bank_mask:0xf
	v_fmac_f32_dpp v184, v122, v98 row_shr:2 row_mask:0xf bank_mask:0xf
	v_fmac_f32_dpp v185, v123, v99 row_shr:2 row_mask:0xf bank_mask:0xf
	v_fmac_f32_dpp v186, v124, v100 row_shr:2 row_mask:0xf bank_mask:0xf
	v_fmac_f32_dpp v187, v125, v101 row_shr:2 row_mask:0xf bank_mask:0xf
	v_fmac_f32_dpp v180, v134, v82 row_shl:14 row_mask:0xf bank_mask:0xf
	v_fmac_f32_dpp v181, v135, v83 row_shl:14 row_mask:0xf bank_mask:0xf
	v_fmac_f32_dpp v182, v136, v84 row_shl:14 row_mask:0xf bank_mask:0xf
	v_fmac_f32_dpp v183, v137, v85 row_shl:14 row_mask:0xf bank_mask:0xf
	v_fmac_f32_dpp v184, v130, v98 row_shl:14 row_mask:0xf bank_mask:0xf
	v_fmac_f32_dpp v185, v131, v99 row_shl:14 row_mask:0xf bank_mask:0xf
	v_fmac_f32_dpp v186, v132, v100 row_shl:14 row_mask:0xf bank_mask:0xf
	v_fmac_f32_dpp v187, v133, v101 row_shl:14 row_mask:0xf bank_mask:0xf
	v_fmac_f32_dpp v180, v126, v86 row_shr:1 row_mask:0xf bank_mask:0xf
	v_fmac_f32_dpp v181, v127, v87 row_shr:1 row_mask:0xf bank_mask:0xf
	v_fmac_f32_dpp v182, v128, v88 row_shr:1 row_mask:0xf bank_mask:0xf
	v_fmac_f32_dpp v183, v129, v89 row_shr:1 row_mask:0xf bank_mask:0xf
	v_fmac_f32_dpp v184, v122, v102 row_shr:1 row_mask:0xf bank_mask:0xf
	v_fmac_f32_dpp v185, v123, v103 row_shr:1 row_mask:0xf bank_mask:0xf
	v_fmac_f32_dpp v186, v124, v104 row_shr:1 row_mask:0xf bank_mask:0xf
	v_fmac_f32_dpp v187, v125, v105 row_shr:1 row_mask:0xf bank_mask:0xf
	v_fmac_f32_dpp v180, v134, v86 row_shl:15 row_mask:0xf bank_mask:0xf
	v_fmac_f32_dpp v181, v135, v87 row_shl:15 row_mask:0xf bank_mask:0xf
	v_fmac_f32_dpp v182, v136, v88 row_shl:15 row_mask:0xf bank_mask:0xf
	v_fmac_f32_dpp v183, v137, v89 row_shl:15 row_mask:0xf bank_mask:0xf
	v_fmac_f32_dpp v184, v130, v102 row_shl:15 row_mask:0xf bank_mask:0xf
	v_fmac_f32_dpp v185, v131, v103 row_shl:15 row_mask:0xf bank_mask:0xf
	v_fmac_f32_dpp v186, v132, v104 row_shl:15 row_mask:0xf bank_mask:0xf
	v_fmac_f32_dpp v187, v133, v105 row_shl:15 row_mask:0xf bank_mask:0xf
	v_pk_fma_f32 v[180:181], v[126:127], v[90:91], v[180:181]
	v_pk_fma_f32 v[182:183], v[128:129], v[92:93], v[182:183]
	v_pk_fma_f32 v[184:185], v[122:123], v[106:107], v[184:185]
	v_pk_fma_f32 v[186:187], v[124:125], v[108:109], v[186:187]
	v_mul_f32_e32 v188, 0xbfb8aa3b, v180
	v_mul_f32_e32 v189, 0xbfb8aa3b, v181
	v_mul_f32_e32 v190, 0xbfb8aa3b, v182
	v_mul_f32_e32 v191, 0xbfb8aa3b, v183
	v_exp_f32_e32 v188, v188
	v_exp_f32_e32 v189, v189
	v_exp_f32_e32 v190, v190
	v_exp_f32_e32 v191, v191
	v_add_f32_e32 v188, 1.0, v188
	v_add_f32_e32 v189, 1.0, v189
	v_add_f32_e32 v190, 1.0, v190
	v_add_f32_e32 v191, 1.0, v191
	v_rcp_f32_e32 v188, v188
	v_rcp_f32_e32 v189, v189
	v_rcp_f32_e32 v190, v190
	v_rcp_f32_e32 v191, v191
	v_cmp_gt_i32_e32 vcc, 0x3fc0, v230
	v_pk_mul_f32 v[188:189], v[180:181], v[188:189]
	v_pk_mul_f32 v[190:191], v[182:183], v[190:191]
	v_pk_mul_f32 v[188:189], v[184:185], v[188:189]
	v_pk_mul_f32 v[190:191], v[186:187], v[190:191]
	v_add_u32_e32 v234, 0x58000, v233
	v_cvt_pk_bf16_f32 v206, v188, v189
	v_cvt_pk_bf16_f32 v207, v190, v191
	s_and_saveexec_b64 s[4:5], vcc
	s_cbranch_execz .Lupepi_skip4
	global_store_dwordx2 v234, v[206:207], s[26:27]
.Lupepi_skip4:
	s_or_b64 exec, exec, s[4:5]
	global_load_dwordx4 v[158:161], v232, s[30:31] offset:16
	global_load_dwordx4 v[154:157], v232, s[38:39] offset:16
	global_load_dwordx4 v[150:153], v232, s[40:41] offset:16
	global_load_dwordx4 v[146:149], v232, s[34:35] offset:16
	global_load_dwordx4 v[142:145], v232, s[42:43] offset:16
	global_load_dwordx4 v[138:141], v232, s[44:45] offset:16
	global_load_dwordx4 v[134:137], v232, s[46:47] offset:16
	global_load_dwordx4 v[130:133], v232, s[48:49] offset:16
	v_pk_mul_f32 v[118:119], v[118:119], v[176:177] op_sel:[0,1] op_sel_hi:[1,1]
	v_pk_mul_f32 v[120:121], v[120:121], v[176:177] op_sel:[0,1] op_sel_hi:[1,1]
	v_pk_mul_f32 v[114:115], v[114:115], v[176:177] op_sel:[0,1] op_sel_hi:[1,1]
	v_pk_mul_f32 v[116:117], v[116:117], v[176:177] op_sel:[0,1] op_sel_hi:[1,1]
	v_mov_b32_e32 v180, v94
	v_mov_b32_e32 v181, v95
	v_mov_b32_e32 v182, v96
	v_mov_b32_e32 v183, v97
	v_mov_b32_e32 v184, v110
	v_mov_b32_e32 v185, v111
	v_mov_b32_e32 v186, v112
	v_mov_b32_e32 v187, v113
	v_fmac_f32_dpp v180, v118, v82 row_shr:2 row_mask:0xf bank_mask:0xf
	v_fmac_f32_dpp v181, v119, v83 row_shr:2 row_mask:0xf bank_mask:0xf
	v_fmac_f32_dpp v182, v120, v84 row_shr:2 row_mask:0xf bank_mask:0xf
	v_fmac_f32_dpp v183, v121, v85 row_shr:2 row_mask:0xf bank_mask:0xf
	v_fmac_f32_dpp v184, v114, v98 row_shr:2 row_mask:0xf bank_mask:0xf
	v_fmac_f32_dpp v185, v115, v99 row_shr:2 row_mask:0xf bank_mask:0xf
	v_fmac_f32_dpp v186, v116, v100 row_shr:2 row_mask:0xf bank_mask:0xf
	v_fmac_f32_dpp v187, v117, v101 row_shr:2 row_mask:0xf bank_mask:0xf
	v_fmac_f32_dpp v180, v126, v82 row_shl:14 row_mask:0xf bank_mask:0xf
	v_fmac_f32_dpp v181, v127, v83 row_shl:14 row_mask:0xf bank_mask:0xf
; __device__ __forceinline__ void store4(bf16_t* p, f32x4 v) { u32x2 w; w.x = cvt_pk_bf16(v[0], v[1]); w.y = cvt_pk_bf16(v[2], v[3]); *(u32x2*)p = w; }
; __device__ __forceinline__ float dpp_ror1(float x) { float r; asm volatile("s_nop 1\n\tv_mov_b32_dpp %0, %1 row_ror:1 row_mask:0xf bank_mask:0xf" : "=v"(r) : "v"(x)); return r; }
; __device__ __forceinline__ float dpp_ror2(float x) { float r; asm volatile("s_nop 1\n\tv_mov_b32_dpp %0, %1 row_ror:2 row_mask:0xf bank_mask:0xf" : "=v"(r) : "v"(x)); return r; }
;     __device__ __forceinline__ void operator()(const f32x4 (&acc)[2][2][4][2], const Unit& u, int wr, int wc, int fr, int fq) const {
;     ...
;             for (int q = 0; q < 8; ++q) {
;                 const f32x4 ug = acc[q >> 2][0][q & 3][n] * rs[q], uv = acc[q >> 2][1][q & 3][n] * rs[q];
;                 f32x4 res;
; #pragma unroll
;                 for (int j = 0; j < 4; ++j) {
;                     const float ga1 = dpp_ror1(ug[j]), gb1 = dpp_ror1(pg[j]), ga2 = dpp_ror2(ug[j]), gb2 = dpp_ror2(pg[j]);
;                     const float va1 = dpp_ror1(uv[j]), vb1 = dpp_ror1(pv[j]), va2 = dpp_ror2(uv[j]), vb2 = dpp_ror2(pv[j]);
;                     const float g1 = fr >= 1 ? ga1 : gb1, g2 = fr >= 2 ? ga2 : gb2, v1 = fr >= 1 ? va1 : vb1, v2 = fr >= 2 ? va2 : vb2;
;                     const float cgv = bg[j] + wg0[j] * g2 + wg1[j] * g1 + wg2[j] * ug[j];
;                     const float cvv = bv[j] + wv0[j] * v2 + wv1[j] * v1 + wv2[j] * uv[j];
;                     res[j] = cgv * __builtin_amdgcn_rcpf(1.0f + __builtin_amdgcn_exp2f(-1.44269504f * cgv)) * cvv;
;                 }
;                 pg = ug; pv = uv;
;                 const int row = g0 + 16 * q;
;                 if ((q > 0 || fr >= 2) && row < SEQ) store4(ACT + (size_t)row * 2816 + col, res);
	v_fmac_f32_dpp v182, v128, v84 row_shl:14 row_mask:0xf bank_mask:0xf
	v_fmac_f32_dpp v183, v129, v85 row_shl:14 row_mask:0xf bank_mask:0xf
	v_fmac_f32_dpp v184, v122, v98 row_shl:14 row_mask:0xf bank_mask:0xf
	v_fmac_f32_dpp v185, v123, v99 row_shl:14 row_mask:0xf bank_mask:0xf
	v_fmac_f32_dpp v186, v124, v100 row_shl:14 row_mask:0xf bank_mask:0xf
	v_fmac_f32_dpp v187, v125, v101 row_shl:14 row_mask:0xf bank_mask:0xf
	v_fmac_f32_dpp v180, v118, v86 row_shr:1 row_mask:0xf bank_mask:0xf
	v_fmac_f32_dpp v181, v119, v87 row_shr:1 row_mask:0xf bank_mask:0xf
	v_fmac_f32_dpp v182, v120, v88 row_shr:1 row_mask:0xf bank_mask:0xf
	v_fmac_f32_dpp v183, v121, v89 row_shr:1 row_mask:0xf bank_mask:0xf
	v_fmac_f32_dpp v184, v114, v102 row_shr:1 row_mask:0xf bank_mask:0xf
	v_fmac_f32_dpp v185, v115, v103 row_shr:1 row_mask:0xf bank_mask:0xf
	v_fmac_f32_dpp v186, v116, v104 row_shr:1 row_mask:0xf bank_mask:0xf
	v_fmac_f32_dpp v187, v117, v105 row_shr:1 row_mask:0xf bank_mask:0xf
	v_fmac_f32_dpp v180, v126, v86 row_shl:15 row_mask:0xf bank_mask:0xf
	v_fmac_f32_dpp v181, v127, v87 row_shl:15 row_mask:0xf bank_mask:0xf
	v_fmac_f32_dpp v182, v128, v88 row_shl:15 row_mask:0xf bank_mask:0xf
	v_fmac_f32_dpp v183, v129, v89 row_shl:15 row_mask:0xf bank_mask:0xf
	v_fmac_f32_dpp v184, v122, v102 row_shl:15 row_mask:0xf bank_mask:0xf
	v_fmac_f32_dpp v185, v123, v103 row_shl:15 row_mask:0xf bank_mask:0xf
	v_fmac_f32_dpp v186, v124, v104 row_shl:15 row_mask:0xf bank_mask:0xf
	v_fmac_f32_dpp v187, v125, v105 row_shl:15 row_mask:0xf bank_mask:0xf
	v_pk_fma_f32 v[180:181], v[118:119], v[90:91], v[180:181]
	v_pk_fma_f32 v[182:183], v[120:121], v[92:93], v[182:183]
	v_pk_fma_f32 v[184:185], v[114:115], v[106:107], v[184:185]
	v_pk_fma_f32 v[186:187], v[116:117], v[108:109], v[186:187]
	v_mul_f32_e32 v188, 0xbfb8aa3b, v180
	v_mul_f32_e32 v189, 0xbfb8aa3b, v181
	v_mul_f32_e32 v190, 0xbfb8aa3b, v182
	v_mul_f32_e32 v191, 0xbfb8aa3b, v183
	v_exp_f32_e32 v188, v188
	v_exp_f32_e32 v189, v189
	v_exp_f32_e32 v190, v190
	v_exp_f32_e32 v191, v191
	v_add_f32_e32 v188, 1.0, v188
	v_add_f32_e32 v189, 1.0, v189
	v_add_f32_e32 v190, 1.0, v190
	v_add_f32_e32 v191, 1.0, v191
	v_rcp_f32_e32 v188, v188
	v_rcp_f32_e32 v189, v189
	v_rcp_f32_e32 v190, v190
	v_rcp_f32_e32 v191, v191
	v_cmp_gt_i32_e32 vcc, 0x3fb0, v230
	v_pk_mul_f32 v[188:189], v[180:181], v[188:189]
	v_pk_mul_f32 v[190:191], v[182:183], v[190:191]
	v_pk_mul_f32 v[188:189], v[184:185], v[188:189]
	v_pk_mul_f32 v[190:191], v[186:187], v[190:191]
	v_add_u32_e32 v234, 0x6e000, v233
	v_cvt_pk_bf16_f32 v208, v188, v189
	v_cvt_pk_bf16_f32 v209, v190, v191
	s_and_saveexec_b64 s[4:5], vcc
	s_cbranch_execz .Lupepi_skip5
	global_store_dwordx2 v234, v[208:209], s[26:27]
.Lupepi_skip5:
	s_or_b64 exec, exec, s[4:5]
	v_pk_mul_f32 v[78:79], v[78:79], v[178:179] op_sel_hi:[1,0]
	v_pk_mul_f32 v[80:81], v[80:81], v[178:179] op_sel_hi:[1,0]
	v_pk_mul_f32 v[74:75], v[74:75], v[178:179] op_sel_hi:[1,0]
	v_pk_mul_f32 v[76:77], v[76:77], v[178:179] op_sel_hi:[1,0]
	v_mov_b32_e32 v180, v94
	v_mov_b32_e32 v181, v95
	v_mov_b32_e32 v182, v96
	v_mov_b32_e32 v183, v97
	v_mov_b32_e32 v184, v110
	v_mov_b32_e32 v185, v111
	v_mov_b32_e32 v186, v112
	v_mov_b32_e32 v187, v113
	v_fmac_f32_dpp v180, v78, v82 row_shr:2 row_mask:0xf bank_mask:0xf
	v_fmac_f32_dpp v181, v79, v83 row_shr:2 row_mask:0xf bank_mask:0xf
	v_fmac_f32_dpp v182, v80, v84 row_shr:2 row_mask:0xf bank_mask:0xf
	v_fmac_f32_dpp v183, v81, v85 row_shr:2 row_mask:0xf bank_mask:0xf
	v_fmac_f32_dpp v184, v74, v98 row_shr:2 row_mask:0xf bank_mask:0xf
	v_fmac_f32_dpp v185, v75, v99 row_shr:2 row_mask:0xf bank_mask:0xf
	v_fmac_f32_dpp v186, v76, v100 row_shr:2 row_mask:0xf bank_mask:0xf
	v_fmac_f32_dpp v187, v77, v101 row_shr:2 row_mask:0xf bank_mask:0xf
	v_fmac_f32_dpp v180, v118, v82 row_shl:14 row_mask:0xf bank_mask:0xf
	v_fmac_f32_dpp v181, v119, v83 row_shl:14 row_mask:0xf bank_mask:0xf
	v_fmac_f32_dpp v182, v120, v84 row_shl:14 row_mask:0xf bank_mask:0xf
	v_fmac_f32_dpp v183, v121, v85 row_shl:14 row_mask:0xf bank_mask:0xf
	v_fmac_f32_dpp v184, v114, v98 row_shl:14 row_mask:0xf bank_mask:0xf
	v_fmac_f32_dpp v185, v115, v99 row_shl:14 row_mask:0xf bank_mask:0xf
	v_fmac_f32_dpp v186, v116, v100 row_shl:14 row_mask:0xf bank_mask:0xf
	v_fmac_f32_dpp v187, v117, v101 row_shl:14 row_mask:0xf bank_mask:0xf
	v_fmac_f32_dpp v180, v78, v86 row_shr:1 row_mask:0xf bank_mask:0xf
	v_fmac_f32_dpp v181, v79, v87 row_shr:1 row_mask:0xf bank_mask:0xf
	v_fmac_f32_dpp v182, v80, v88 row_shr:1 row_mask:0xf bank_mask:0xf
	v_fmac_f32_dpp v183, v81, v89 row_shr:1 row_mask:0xf bank_mask:0xf
	v_fmac_f32_dpp v184, v74, v102 row_shr:1 row_mask:0xf bank_mask:0xf
	v_fmac_f32_dpp v185, v75, v103 row_shr:1 row_mask:0xf bank_mask:0xf
	v_fmac_f32_dpp v186, v76, v104 row_shr:1 row_mask:0xf bank_mask:0xf
	v_fmac_f32_dpp v187, v77, v105 row_shr:1 row_mask:0xf bank_mask:0xf
	v_fmac_f32_dpp v180, v118, v86 row_shl:15 row_mask:0xf bank_mask:0xf
	v_fmac_f32_dpp v181, v119, v87 row_shl:15 row_mask:0xf bank_mask:0xf
	v_fmac_f32_dpp v182, v120, v88 row_shl:15 row_mask:0xf bank_mask:0xf
	v_fmac_f32_dpp v183, v121, v89 row_shl:15 row_mask:0xf bank_mask:0xf
	v_fmac_f32_dpp v184, v114, v102 row_shl:15 row_mask:0xf bank_mask:0xf
	v_fmac_f32_dpp v185, v115, v103 row_shl:15 row_mask:0xf bank_mask:0xf
	v_fmac_f32_dpp v186, v116, v104 row_shl:15 row_mask:0xf bank_mask:0xf
	v_fmac_f32_dpp v187, v117, v105 row_shl:15 row_mask:0xf bank_mask:0xf
	v_pk_fma_f32 v[180:181], v[78:79], v[90:91], v[180:181]
	v_pk_fma_f32 v[182:183], v[80:81], v[92:93], v[182:183]
	v_pk_fma_f32 v[184:185], v[74:75], v[106:107], v[184:185]
	v_pk_fma_f32 v[186:187], v[76:77], v[108:109], v[186:187]
	v_mul_f32_e32 v188, 0xbfb8aa3b, v180
	v_mul_f32_e32 v189, 0xbfb8aa3b, v181
	v_mul_f32_e32 v190, 0xbfb8aa3b, v182
	v_mul_f32_e32 v191, 0xbfb8aa3b, v183
	v_exp_f32_e32 v188, v188
	v_exp_f32_e32 v189, v189
	v_exp_f32_e32 v190, v190
	v_exp_f32_e32 v191, v191
	v_add_f32_e32 v188, 1.0, v188
	v_add_f32_e32 v189, 1.0, v189
	v_add_f32_e32 v190, 1.0, v190
	v_add_f32_e32 v191, 1.0, v191
	v_rcp_f32_e32 v188, v188
	v_rcp_f32_e32 v189, v189
	v_rcp_f32_e32 v190, v190
	v_rcp_f32_e32 v191, v191
	v_cmp_gt_i32_e32 vcc, 0x3fa0, v230
	v_pk_mul_f32 v[188:189], v[180:181], v[188:189]
	v_pk_mul_f32 v[190:191], v[182:183], v[190:191]
	v_pk_mul_f32 v[188:189], v[184:185], v[188:189]
	v_pk_mul_f32 v[190:191], v[186:187], v[190:191]
	v_add_u32_e32 v234, 0x84000, v233
	v_cvt_pk_bf16_f32 v206, v188, v189
	v_cvt_pk_bf16_f32 v207, v190, v191
	s_and_saveexec_b64 s[4:5], vcc
	s_cbranch_execz .Lupepi_skip6
	global_store_dwordx2 v234, v[206:207], s[26:27]
; __device__ __forceinline__ void store4(bf16_t* p, f32x4 v) { u32x2 w; w.x = cvt_pk_bf16(v[0], v[1]); w.y = cvt_pk_bf16(v[2], v[3]); *(u32x2*)p = w; }
; __device__ __forceinline__ float dpp_ror1(float x) { float r; asm volatile("s_nop 1\n\tv_mov_b32_dpp %0, %1 row_ror:1 row_mask:0xf bank_mask:0xf" : "=v"(r) : "v"(x)); return r; }
; __device__ __forceinline__ float dpp_ror2(float x) { float r; asm volatile("s_nop 1\n\tv_mov_b32_dpp %0, %1 row_ror:2 row_mask:0xf bank_mask:0xf" : "=v"(r) : "v"(x)); return r; }
;     __device__ __forceinline__ void operator()(const f32x4 (&acc)[2][2][4][2], const Unit& u, int wr, int wc, int fr, int fq) const {
;     ...
;             for (int q = 0; q < 8; ++q) {
;                 const f32x4 ug = acc[q >> 2][0][q & 3][n] * rs[q], uv = acc[q >> 2][1][q & 3][n] * rs[q];
;                 f32x4 res;
; #pragma unroll
;                 for (int j = 0; j < 4; ++j) {
;                     const float ga1 = dpp_ror1(ug[j]), gb1 = dpp_ror1(pg[j]), ga2 = dpp_ror2(ug[j]), gb2 = dpp_ror2(pg[j]);
;                     const float va1 = dpp_ror1(uv[j]), vb1 = dpp_ror1(pv[j]), va2 = dpp_ror2(uv[j]), vb2 = dpp_ror2(pv[j]);
;                     const float g1 = fr >= 1 ? ga1 : gb1, g2 = fr >= 2 ? ga2 : gb2, v1 = fr >= 1 ? va1 : vb1, v2 = fr >= 2 ? va2 : vb2;
;                     const float cgv = bg[j] + wg0[j] * g2 + wg1[j] * g1 + wg2[j] * ug[j];
;                     const float cvv = bv[j] + wv0[j] * v2 + wv1[j] * v1 + wv2[j] * uv[j];
;                     res[j] = cgv * __builtin_amdgcn_rcpf(1.0f + __builtin_amdgcn_exp2f(-1.44269504f * cgv)) * cvv;
;                 }
;                 pg = ug; pv = uv;
;                 const int row = g0 + 16 * q;
;                 if ((q > 0 || fr >= 2) && row < SEQ) store4(ACT + (size_t)row * 2816 + col, res);
.Lupepi_skip6:
	s_or_b64 exec, exec, s[4:5]
	v_pk_mul_f32 v[70:71], v[70:71], v[178:179] op_sel:[0,1] op_sel_hi:[1,1]
	v_pk_mul_f32 v[72:73], v[72:73], v[178:179] op_sel:[0,1] op_sel_hi:[1,1]
	v_pk_mul_f32 v[66:67], v[66:67], v[178:179] op_sel:[0,1] op_sel_hi:[1,1]
	v_pk_mul_f32 v[68:69], v[68:69], v[178:179] op_sel:[0,1] op_sel_hi:[1,1]
	v_mov_b32_e32 v180, v94
	v_mov_b32_e32 v181, v95
	v_mov_b32_e32 v182, v96
	v_mov_b32_e32 v183, v97
	v_mov_b32_e32 v184, v110
	v_mov_b32_e32 v185, v111
	v_mov_b32_e32 v186, v112
	v_mov_b32_e32 v187, v113
	v_fmac_f32_dpp v180, v70, v82 row_shr:2 row_mask:0xf bank_mask:0xf
	v_fmac_f32_dpp v181, v71, v83 row_shr:2 row_mask:0xf bank_mask:0xf
	v_fmac_f32_dpp v182, v72, v84 row_shr:2 row_mask:0xf bank_mask:0xf
	v_fmac_f32_dpp v183, v73, v85 row_shr:2 row_mask:0xf bank_mask:0xf
	v_fmac_f32_dpp v184, v66, v98 row_shr:2 row_mask:0xf bank_mask:0xf
	v_fmac_f32_dpp v185, v67, v99 row_shr:2 row_mask:0xf bank_mask:0xf
	v_fmac_f32_dpp v186, v68, v100 row_shr:2 row_mask:0xf bank_mask:0xf
	v_fmac_f32_dpp v187, v69, v101 row_shr:2 row_mask:0xf bank_mask:0xf
	v_fmac_f32_dpp v180, v78, v82 row_shl:14 row_mask:0xf bank_mask:0xf
	v_fmac_f32_dpp v181, v79, v83 row_shl:14 row_mask:0xf bank_mask:0xf
	v_fmac_f32_dpp v182, v80, v84 row_shl:14 row_mask:0xf bank_mask:0xf
	v_fmac_f32_dpp v183, v81, v85 row_shl:14 row_mask:0xf bank_mask:0xf
	v_fmac_f32_dpp v184, v74, v98 row_shl:14 row_mask:0xf bank_mask:0xf
	v_fmac_f32_dpp v185, v75, v99 row_shl:14 row_mask:0xf bank_mask:0xf
	v_fmac_f32_dpp v186, v76, v100 row_shl:14 row_mask:0xf bank_mask:0xf
	v_fmac_f32_dpp v187, v77, v101 row_shl:14 row_mask:0xf bank_mask:0xf
	v_fmac_f32_dpp v180, v70, v86 row_shr:1 row_mask:0xf bank_mask:0xf
	v_fmac_f32_dpp v181, v71, v87 row_shr:1 row_mask:0xf bank_mask:0xf
	v_fmac_f32_dpp v182, v72, v88 row_shr:1 row_mask:0xf bank_mask:0xf
	v_fmac_f32_dpp v183, v73, v89 row_shr:1 row_mask:0xf bank_mask:0xf
	v_fmac_f32_dpp v184, v66, v102 row_shr:1 row_mask:0xf bank_mask:0xf
	v_fmac_f32_dpp v185, v67, v103 row_shr:1 row_mask:0xf bank_mask:0xf
	v_fmac_f32_dpp v186, v68, v104 row_shr:1 row_mask:0xf bank_mask:0xf
	v_fmac_f32_dpp v187, v69, v105 row_shr:1 row_mask:0xf bank_mask:0xf
	v_fmac_f32_dpp v180, v78, v86 row_shl:15 row_mask:0xf bank_mask:0xf
	v_fmac_f32_dpp v181, v79, v87 row_shl:15 row_mask:0xf bank_mask:0xf
	v_fmac_f32_dpp v182, v80, v88 row_shl:15 row_mask:0xf bank_mask:0xf
	v_fmac_f32_dpp v183, v81, v89 row_shl:15 row_mask:0xf bank_mask:0xf
	v_fmac_f32_dpp v184, v74, v102 row_shl:15 row_mask:0xf bank_mask:0xf
	v_fmac_f32_dpp v185, v75, v103 row_shl:15 row_mask:0xf bank_mask:0xf
	v_fmac_f32_dpp v186, v76, v104 row_shl:15 row_mask:0xf bank_mask:0xf
	v_fmac_f32_dpp v187, v77, v105 row_shl:15 row_mask:0xf bank_mask:0xf
	v_pk_fma_f32 v[180:181], v[70:71], v[90:91], v[180:181]
	v_pk_fma_f32 v[182:183], v[72:73], v[92:93], v[182:183]
	v_pk_fma_f32 v[184:185], v[66:67], v[106:107], v[184:185]
	v_pk_fma_f32 v[186:187], v[68:69], v[108:109], v[186:187]
	v_mul_f32_e32 v188, 0xbfb8aa3b, v180
	v_mul_f32_e32 v189, 0xbfb8aa3b, v181
	v_mul_f32_e32 v190, 0xbfb8aa3b, v182
	v_mul_f32_e32 v191, 0xbfb8aa3b, v183
	v_exp_f32_e32 v188, v188
	v_exp_f32_e32 v189, v189
	v_exp_f32_e32 v190, v190
	v_exp_f32_e32 v191, v191
	v_add_f32_e32 v188, 1.0, v188
	v_add_f32_e32 v189, 1.0, v189
	v_add_f32_e32 v190, 1.0, v190
	v_add_f32_e32 v191, 1.0, v191
	v_rcp_f32_e32 v188, v188
	v_rcp_f32_e32 v189, v189
	v_rcp_f32_e32 v190, v190
	v_rcp_f32_e32 v191, v191
	v_cmp_gt_i32_e32 vcc, 0x3f90, v230
	v_pk_mul_f32 v[188:189], v[180:181], v[188:189]
	v_pk_mul_f32 v[190:191], v[182:183], v[190:191]
	v_pk_mul_f32 v[188:189], v[184:185], v[188:189]
	v_pk_mul_f32 v[190:191], v[186:187], v[190:191]
	v_add_u32_e32 v234, 0x9a000, v233
	v_cvt_pk_bf16_f32 v208, v188, v189
	v_cvt_pk_bf16_f32 v209, v190, v191
	s_and_saveexec_b64 s[4:5], vcc
	s_cbranch_execz .Lupepi_skip7
	global_store_dwordx2 v234, v[208:209], s[26:27]
.Lupepi_skip7:
	s_or_b64 exec, exec, s[4:5]
	s_waitcnt vmcnt(0)
	v_pk_mul_f32 v[62:63], v[62:63], v[172:173] op_sel_hi:[1,0]
	v_pk_mul_f32 v[64:65], v[64:65], v[172:173] op_sel_hi:[1,0]
	v_pk_mul_f32 v[58:59], v[58:59], v[172:173] op_sel_hi:[1,0]
	v_pk_mul_f32 v[60:61], v[60:61], v[172:173] op_sel_hi:[1,0]
	v_mov_b32_e32 v180, v146
	v_mov_b32_e32 v181, v147
	v_mov_b32_e32 v182, v148
	v_mov_b32_e32 v183, v149
	v_mov_b32_e32 v184, v130
	v_mov_b32_e32 v185, v131
	v_mov_b32_e32 v186, v132
	v_mov_b32_e32 v187, v133
	v_fmac_f32_dpp v180, v62, v158 row_shr:2 row_mask:0xf bank_mask:0xf
	v_fmac_f32_dpp v181, v63, v159 row_shr:2 row_mask:0xf bank_mask:0xf
	v_fmac_f32_dpp v182, v64, v160 row_shr:2 row_mask:0xf bank_mask:0xf
	v_fmac_f32_dpp v183, v65, v161 row_shr:2 row_mask:0xf bank_mask:0xf
	v_fmac_f32_dpp v184, v58, v142 row_shr:2 row_mask:0xf bank_mask:0xf
	v_fmac_f32_dpp v185, v59, v143 row_shr:2 row_mask:0xf bank_mask:0xf
	v_fmac_f32_dpp v186, v60, v144 row_shr:2 row_mask:0xf bank_mask:0xf
	v_fmac_f32_dpp v187, v61, v145 row_shr:2 row_mask:0xf bank_mask:0xf
	v_fmac_f32_dpp v180, v62, v154 row_shr:1 row_mask:0xf bank_mask:0xf
	v_fmac_f32_dpp v181, v63, v155 row_shr:1 row_mask:0xf bank_mask:0xf
	v_fmac_f32_dpp v182, v64, v156 row_shr:1 row_mask:0xf bank_mask:0xf
	v_fmac_f32_dpp v183, v65, v157 row_shr:1 row_mask:0xf bank_mask:0xf
	v_fmac_f32_dpp v184, v58, v138 row_shr:1 row_mask:0xf bank_mask:0xf
	v_fmac_f32_dpp v185, v59, v139 row_shr:1 row_mask:0xf bank_mask:0xf
	v_fmac_f32_dpp v186, v60, v140 row_shr:1 row_mask:0xf bank_mask:0xf
	v_fmac_f32_dpp v187, v61, v141 row_shr:1 row_mask:0xf bank_mask:0xf
	v_pk_fma_f32 v[180:181], v[62:63], v[150:151], v[180:181]
	v_pk_fma_f32 v[182:183], v[64:65], v[152:153], v[182:183]
	v_pk_fma_f32 v[184:185], v[58:59], v[134:135], v[184:185]
	v_pk_fma_f32 v[186:187], v[60:61], v[136:137], v[186:187]
	v_mul_f32_e32 v188, 0xbfb8aa3b, v180
	v_mul_f32_e32 v189, 0xbfb8aa3b, v181
	v_mul_f32_e32 v190, 0xbfb8aa3b, v182
	v_mul_f32_e32 v191, 0xbfb8aa3b, v183
	v_exp_f32_e32 v188, v188
	v_exp_f32_e32 v189, v189
	v_exp_f32_e32 v190, v190
	v_exp_f32_e32 v191, v191
	v_add_f32_e32 v188, 1.0, v188
	v_add_f32_e32 v189, 1.0, v189
	v_add_f32_e32 v190, 1.0, v190
	v_add_f32_e32 v191, 1.0, v191
	v_rcp_f32_e32 v188, v188
	v_rcp_f32_e32 v189, v189
	v_rcp_f32_e32 v190, v190
	v_rcp_f32_e32 v191, v191
	v_cmp_gt_i32_e32 vcc, 0x4000, v230
	v_pk_mul_f32 v[188:189], v[180:181], v[188:189]
	v_pk_mul_f32 v[190:191], v[182:183], v[190:191]
	v_pk_mul_f32 v[188:189], v[184:185], v[188:189]
	v_pk_mul_f32 v[190:191], v[186:187], v[190:191]
	s_and_b64 vcc, vcc, s[8:9]
	v_cvt_pk_bf16_f32 v206, v188, v189
	v_cvt_pk_bf16_f32 v207, v190, v191
	s_and_saveexec_b64 s[4:5], vcc
	s_cbranch_execz .Lupepi_skip8
	global_store_dwordx2 v233, v[206:207], s[26:27] offset:8
; __device__ __forceinline__ void store4(bf16_t* p, f32x4 v) { u32x2 w; w.x = cvt_pk_bf16(v[0], v[1]); w.y = cvt_pk_bf16(v[2], v[3]); *(u32x2*)p = w; }
; __device__ __forceinline__ float dpp_ror1(float x) { float r; asm volatile("s_nop 1\n\tv_mov_b32_dpp %0, %1 row_ror:1 row_mask:0xf bank_mask:0xf" : "=v"(r) : "v"(x)); return r; }
; __device__ __forceinline__ float dpp_ror2(float x) { float r; asm volatile("s_nop 1\n\tv_mov_b32_dpp %0, %1 row_ror:2 row_mask:0xf bank_mask:0xf" : "=v"(r) : "v"(x)); return r; }
;     __device__ __forceinline__ void operator()(const f32x4 (&acc)[2][2][4][2], const Unit& u, int wr, int wc, int fr, int fq) const {
;     ...
;             for (int q = 0; q < 8; ++q) {
;                 const f32x4 ug = acc[q >> 2][0][q & 3][n] * rs[q], uv = acc[q >> 2][1][q & 3][n] * rs[q];
;                 f32x4 res;
; #pragma unroll
;                 for (int j = 0; j < 4; ++j) {
;                     const float ga1 = dpp_ror1(ug[j]), gb1 = dpp_ror1(pg[j]), ga2 = dpp_ror2(ug[j]), gb2 = dpp_ror2(pg[j]);
;                     const float va1 = dpp_ror1(uv[j]), vb1 = dpp_ror1(pv[j]), va2 = dpp_ror2(uv[j]), vb2 = dpp_ror2(pv[j]);
;                     const float g1 = fr >= 1 ? ga1 : gb1, g2 = fr >= 2 ? ga2 : gb2, v1 = fr >= 1 ? va1 : vb1, v2 = fr >= 2 ? va2 : vb2;
;                     const float cgv = bg[j] + wg0[j] * g2 + wg1[j] * g1 + wg2[j] * ug[j];
;                     const float cvv = bv[j] + wv0[j] * v2 + wv1[j] * v1 + wv2[j] * uv[j];
;                     res[j] = cgv * __builtin_amdgcn_rcpf(1.0f + __builtin_amdgcn_exp2f(-1.44269504f * cgv)) * cvv;
;                 }
;                 pg = ug; pv = uv;
;                 const int row = g0 + 16 * q;
;                 if ((q > 0 || fr >= 2) && row < SEQ) store4(ACT + (size_t)row * 2816 + col, res);
.Lupepi_skip8:
	s_or_b64 exec, exec, s[4:5]
	v_pk_mul_f32 v[54:55], v[54:55], v[172:173] op_sel:[0,1] op_sel_hi:[1,1]
	v_pk_mul_f32 v[56:57], v[56:57], v[172:173] op_sel:[0,1] op_sel_hi:[1,1]
	v_pk_mul_f32 v[50:51], v[50:51], v[172:173] op_sel:[0,1] op_sel_hi:[1,1]
	v_pk_mul_f32 v[52:53], v[52:53], v[172:173] op_sel:[0,1] op_sel_hi:[1,1]
	v_mov_b32_e32 v180, v146
	v_mov_b32_e32 v181, v147
	v_mov_b32_e32 v182, v148
	v_mov_b32_e32 v183, v149
	v_mov_b32_e32 v184, v130
	v_mov_b32_e32 v185, v131
	v_mov_b32_e32 v186, v132
	v_mov_b32_e32 v187, v133
	v_fmac_f32_dpp v180, v54, v158 row_shr:2 row_mask:0xf bank_mask:0xf
	v_fmac_f32_dpp v181, v55, v159 row_shr:2 row_mask:0xf bank_mask:0xf
	v_fmac_f32_dpp v182, v56, v160 row_shr:2 row_mask:0xf bank_mask:0xf
	v_fmac_f32_dpp v183, v57, v161 row_shr:2 row_mask:0xf bank_mask:0xf
	v_fmac_f32_dpp v184, v50, v142 row_shr:2 row_mask:0xf bank_mask:0xf
	v_fmac_f32_dpp v185, v51, v143 row_shr:2 row_mask:0xf bank_mask:0xf
	v_fmac_f32_dpp v186, v52, v144 row_shr:2 row_mask:0xf bank_mask:0xf
	v_fmac_f32_dpp v187, v53, v145 row_shr:2 row_mask:0xf bank_mask:0xf
	v_fmac_f32_dpp v180, v62, v158 row_shl:14 row_mask:0xf bank_mask:0xf
	v_fmac_f32_dpp v181, v63, v159 row_shl:14 row_mask:0xf bank_mask:0xf
	v_fmac_f32_dpp v182, v64, v160 row_shl:14 row_mask:0xf bank_mask:0xf
	v_fmac_f32_dpp v183, v65, v161 row_shl:14 row_mask:0xf bank_mask:0xf
	v_fmac_f32_dpp v184, v58, v142 row_shl:14 row_mask:0xf bank_mask:0xf
	v_fmac_f32_dpp v185, v59, v143 row_shl:14 row_mask:0xf bank_mask:0xf
	v_fmac_f32_dpp v186, v60, v144 row_shl:14 row_mask:0xf bank_mask:0xf
	v_fmac_f32_dpp v187, v61, v145 row_shl:14 row_mask:0xf bank_mask:0xf
	v_fmac_f32_dpp v180, v54, v154 row_shr:1 row_mask:0xf bank_mask:0xf
	v_fmac_f32_dpp v181, v55, v155 row_shr:1 row_mask:0xf bank_mask:0xf
	v_fmac_f32_dpp v182, v56, v156 row_shr:1 row_mask:0xf bank_mask:0xf
	v_fmac_f32_dpp v183, v57, v157 row_shr:1 row_mask:0xf bank_mask:0xf
	v_fmac_f32_dpp v184, v50, v138 row_shr:1 row_mask:0xf bank_mask:0xf
	v_fmac_f32_dpp v185, v51, v139 row_shr:1 row_mask:0xf bank_mask:0xf
	v_fmac_f32_dpp v186, v52, v140 row_shr:1 row_mask:0xf bank_mask:0xf
	v_fmac_f32_dpp v187, v53, v141 row_shr:1 row_mask:0xf bank_mask:0xf
	v_fmac_f32_dpp v180, v62, v154 row_shl:15 row_mask:0xf bank_mask:0xf
	v_fmac_f32_dpp v181, v63, v155 row_shl:15 row_mask:0xf bank_mask:0xf
	v_fmac_f32_dpp v182, v64, v156 row_shl:15 row_mask:0xf bank_mask:0xf
	v_fmac_f32_dpp v183, v65, v157 row_shl:15 row_mask:0xf bank_mask:0xf
	v_fmac_f32_dpp v184, v58, v138 row_shl:15 row_mask:0xf bank_mask:0xf
	v_fmac_f32_dpp v185, v59, v139 row_shl:15 row_mask:0xf bank_mask:0xf
	v_fmac_f32_dpp v186, v60, v140 row_shl:15 row_mask:0xf bank_mask:0xf
	v_fmac_f32_dpp v187, v61, v141 row_shl:15 row_mask:0xf bank_mask:0xf
	v_pk_fma_f32 v[180:181], v[54:55], v[150:151], v[180:181]
	v_pk_fma_f32 v[182:183], v[56:57], v[152:153], v[182:183]
	v_pk_fma_f32 v[184:185], v[50:51], v[134:135], v[184:185]
	v_pk_fma_f32 v[186:187], v[52:53], v[136:137], v[186:187]
	v_mul_f32_e32 v188, 0xbfb8aa3b, v180
	v_mul_f32_e32 v189, 0xbfb8aa3b, v181
	v_mul_f32_e32 v190, 0xbfb8aa3b, v182
	v_mul_f32_e32 v191, 0xbfb8aa3b, v183
	v_exp_f32_e32 v188, v188
	v_exp_f32_e32 v189, v189
	v_exp_f32_e32 v190, v190
	v_exp_f32_e32 v191, v191
	v_add_f32_e32 v188, 1.0, v188
	v_add_f32_e32 v189, 1.0, v189
	v_add_f32_e32 v190, 1.0, v190
	v_add_f32_e32 v191, 1.0, v191
	v_rcp_f32_e32 v188, v188
	v_rcp_f32_e32 v189, v189
	v_rcp_f32_e32 v190, v190
	v_rcp_f32_e32 v191, v191
	v_cmp_gt_i32_e32 vcc, 0x3ff0, v230
	v_pk_mul_f32 v[188:189], v[180:181], v[188:189]
	v_pk_mul_f32 v[190:191], v[182:183], v[190:191]
	v_pk_mul_f32 v[188:189], v[184:185], v[188:189]
	v_pk_mul_f32 v[190:191], v[186:187], v[190:191]
	v_add_u32_e32 v234, 0x16000, v233
	v_cvt_pk_bf16_f32 v208, v188, v189
	v_cvt_pk_bf16_f32 v209, v190, v191
	s_and_saveexec_b64 s[4:5], vcc
	s_cbranch_execz .Lupepi_skip9
	global_store_dwordx2 v234, v[208:209], s[26:27] offset:8
.Lupepi_skip9:
	s_or_b64 exec, exec, s[4:5]
	v_pk_mul_f32 v[46:47], v[46:47], v[174:175] op_sel_hi:[1,0]
	v_pk_mul_f32 v[48:49], v[48:49], v[174:175] op_sel_hi:[1,0]
	v_pk_mul_f32 v[42:43], v[42:43], v[174:175] op_sel_hi:[1,0]
	v_pk_mul_f32 v[44:45], v[44:45], v[174:175] op_sel_hi:[1,0]
	v_mov_b32_e32 v180, v146
	v_mov_b32_e32 v181, v147
	v_mov_b32_e32 v182, v148
	v_mov_b32_e32 v183, v149
	v_mov_b32_e32 v184, v130
	v_mov_b32_e32 v185, v131
	v_mov_b32_e32 v186, v132
	v_mov_b32_e32 v187, v133
	v_fmac_f32_dpp v180, v46, v158 row_shr:2 row_mask:0xf bank_mask:0xf
	v_fmac_f32_dpp v181, v47, v159 row_shr:2 row_mask:0xf bank_mask:0xf
	v_fmac_f32_dpp v182, v48, v160 row_shr:2 row_mask:0xf bank_mask:0xf
	v_fmac_f32_dpp v183, v49, v161 row_shr:2 row_mask:0xf bank_mask:0xf
	v_fmac_f32_dpp v184, v42, v142 row_shr:2 row_mask:0xf bank_mask:0xf
	v_fmac_f32_dpp v185, v43, v143 row_shr:2 row_mask:0xf bank_mask:0xf
	v_fmac_f32_dpp v186, v44, v144 row_shr:2 row_mask:0xf bank_mask:0xf
	v_fmac_f32_dpp v187, v45, v145 row_shr:2 row_mask:0xf bank_mask:0xf
	v_fmac_f32_dpp v180, v54, v158 row_shl:14 row_mask:0xf bank_mask:0xf
	v_fmac_f32_dpp v181, v55, v159 row_shl:14 row_mask:0xf bank_mask:0xf
	v_fmac_f32_dpp v182, v56, v160 row_shl:14 row_mask:0xf bank_mask:0xf
	v_fmac_f32_dpp v183, v57, v161 row_shl:14 row_mask:0xf bank_mask:0xf
	v_fmac_f32_dpp v184, v50, v142 row_shl:14 row_mask:0xf bank_mask:0xf
	v_fmac_f32_dpp v185, v51, v143 row_shl:14 row_mask:0xf bank_mask:0xf
	v_fmac_f32_dpp v186, v52, v144 row_shl:14 row_mask:0xf bank_mask:0xf
	v_fmac_f32_dpp v187, v53, v145 row_shl:14 row_mask:0xf bank_mask:0xf
	v_fmac_f32_dpp v180, v46, v154 row_shr:1 row_mask:0xf bank_mask:0xf
; __device__ __forceinline__ void store4(bf16_t* p, f32x4 v) { u32x2 w; w.x = cvt_pk_bf16(v[0], v[1]); w.y = cvt_pk_bf16(v[2], v[3]); *(u32x2*)p = w; }
; __device__ __forceinline__ float dpp_ror1(float x) { float r; asm volatile("s_nop 1\n\tv_mov_b32_dpp %0, %1 row_ror:1 row_mask:0xf bank_mask:0xf" : "=v"(r) : "v"(x)); return r; }
; __device__ __forceinline__ float dpp_ror2(float x) { float r; asm volatile("s_nop 1\n\tv_mov_b32_dpp %0, %1 row_ror:2 row_mask:0xf bank_mask:0xf" : "=v"(r) : "v"(x)); return r; }
;     __device__ __forceinline__ void operator()(const f32x4 (&acc)[2][2][4][2], const Unit& u, int wr, int wc, int fr, int fq) const {
;     ...
;             for (int q = 0; q < 8; ++q) {
;                 const f32x4 ug = acc[q >> 2][0][q & 3][n] * rs[q], uv = acc[q >> 2][1][q & 3][n] * rs[q];
;                 f32x4 res;
; #pragma unroll
;                 for (int j = 0; j < 4; ++j) {
;                     const float ga1 = dpp_ror1(ug[j]), gb1 = dpp_ror1(pg[j]), ga2 = dpp_ror2(ug[j]), gb2 = dpp_ror2(pg[j]);
;                     const float va1 = dpp_ror1(uv[j]), vb1 = dpp_ror1(pv[j]), va2 = dpp_ror2(uv[j]), vb2 = dpp_ror2(pv[j]);
;                     const float g1 = fr >= 1 ? ga1 : gb1, g2 = fr >= 2 ? ga2 : gb2, v1 = fr >= 1 ? va1 : vb1, v2 = fr >= 2 ? va2 : vb2;
;                     const float cgv = bg[j] + wg0[j] * g2 + wg1[j] * g1 + wg2[j] * ug[j];
;                     const float cvv = bv[j] + wv0[j] * v2 + wv1[j] * v1 + wv2[j] * uv[j];
;                     res[j] = cgv * __builtin_amdgcn_rcpf(1.0f + __builtin_amdgcn_exp2f(-1.44269504f * cgv)) * cvv;
;                 }
;                 pg = ug; pv = uv;
;                 const int row = g0 + 16 * q;
;                 if ((q > 0 || fr >= 2) && row < SEQ) store4(ACT + (size_t)row * 2816 + col, res);
	v_fmac_f32_dpp v181, v47, v155 row_shr:1 row_mask:0xf bank_mask:0xf
	v_fmac_f32_dpp v182, v48, v156 row_shr:1 row_mask:0xf bank_mask:0xf
	v_fmac_f32_dpp v183, v49, v157 row_shr:1 row_mask:0xf bank_mask:0xf
	v_fmac_f32_dpp v184, v42, v138 row_shr:1 row_mask:0xf bank_mask:0xf
	v_fmac_f32_dpp v185, v43, v139 row_shr:1 row_mask:0xf bank_mask:0xf
	v_fmac_f32_dpp v186, v44, v140 row_shr:1 row_mask:0xf bank_mask:0xf
	v_fmac_f32_dpp v187, v45, v141 row_shr:1 row_mask:0xf bank_mask:0xf
	v_fmac_f32_dpp v180, v54, v154 row_shl:15 row_mask:0xf bank_mask:0xf
	v_fmac_f32_dpp v181, v55, v155 row_shl:15 row_mask:0xf bank_mask:0xf
	v_fmac_f32_dpp v182, v56, v156 row_shl:15 row_mask:0xf bank_mask:0xf
	v_fmac_f32_dpp v183, v57, v157 row_shl:15 row_mask:0xf bank_mask:0xf
	v_fmac_f32_dpp v184, v50, v138 row_shl:15 row_mask:0xf bank_mask:0xf
	v_fmac_f32_dpp v185, v51, v139 row_shl:15 row_mask:0xf bank_mask:0xf
	v_fmac_f32_dpp v186, v52, v140 row_shl:15 row_mask:0xf bank_mask:0xf
	v_fmac_f32_dpp v187, v53, v141 row_shl:15 row_mask:0xf bank_mask:0xf
	v_pk_fma_f32 v[180:181], v[46:47], v[150:151], v[180:181]
	v_pk_fma_f32 v[182:183], v[48:49], v[152:153], v[182:183]
	v_pk_fma_f32 v[184:185], v[42:43], v[134:135], v[184:185]
	v_pk_fma_f32 v[186:187], v[44:45], v[136:137], v[186:187]
	v_mul_f32_e32 v188, 0xbfb8aa3b, v180
	v_mul_f32_e32 v189, 0xbfb8aa3b, v181
	v_mul_f32_e32 v190, 0xbfb8aa3b, v182
	v_mul_f32_e32 v191, 0xbfb8aa3b, v183
	v_exp_f32_e32 v188, v188
	v_exp_f32_e32 v189, v189
	v_exp_f32_e32 v190, v190
	v_exp_f32_e32 v191, v191
	v_add_f32_e32 v188, 1.0, v188
	v_add_f32_e32 v189, 1.0, v189
	v_add_f32_e32 v190, 1.0, v190
	v_add_f32_e32 v191, 1.0, v191
	v_rcp_f32_e32 v188, v188
	v_rcp_f32_e32 v189, v189
	v_rcp_f32_e32 v190, v190
	v_rcp_f32_e32 v191, v191
	v_cmp_gt_i32_e32 vcc, 0x3fe0, v230
	v_pk_mul_f32 v[188:189], v[180:181], v[188:189]
	v_pk_mul_f32 v[190:191], v[182:183], v[190:191]
	v_pk_mul_f32 v[188:189], v[184:185], v[188:189]
	v_pk_mul_f32 v[190:191], v[186:187], v[190:191]
	v_add_u32_e32 v234, 0x2c000, v233
	v_cvt_pk_bf16_f32 v206, v188, v189
	v_cvt_pk_bf16_f32 v207, v190, v191
	s_and_saveexec_b64 s[4:5], vcc
	s_cbranch_execz .Lupepi_skip10
	global_store_dwordx2 v234, v[206:207], s[26:27] offset:8
.Lupepi_skip10:
	s_or_b64 exec, exec, s[4:5]
	v_pk_mul_f32 v[38:39], v[38:39], v[174:175] op_sel:[0,1] op_sel_hi:[1,1]
	v_pk_mul_f32 v[40:41], v[40:41], v[174:175] op_sel:[0,1] op_sel_hi:[1,1]
	v_pk_mul_f32 v[34:35], v[34:35], v[174:175] op_sel:[0,1] op_sel_hi:[1,1]
	v_pk_mul_f32 v[36:37], v[36:37], v[174:175] op_sel:[0,1] op_sel_hi:[1,1]
	v_mov_b32_e32 v180, v146
	v_mov_b32_e32 v181, v147
	v_mov_b32_e32 v182, v148
	v_mov_b32_e32 v183, v149
	v_mov_b32_e32 v184, v130
	v_mov_b32_e32 v185, v131
	v_mov_b32_e32 v186, v132
	v_mov_b32_e32 v187, v133
	v_fmac_f32_dpp v180, v38, v158 row_shr:2 row_mask:0xf bank_mask:0xf
	v_fmac_f32_dpp v181, v39, v159 row_shr:2 row_mask:0xf bank_mask:0xf
	v_fmac_f32_dpp v182, v40, v160 row_shr:2 row_mask:0xf bank_mask:0xf
	v_fmac_f32_dpp v183, v41, v161 row_shr:2 row_mask:0xf bank_mask:0xf
	v_fmac_f32_dpp v184, v34, v142 row_shr:2 row_mask:0xf bank_mask:0xf
	v_fmac_f32_dpp v185, v35, v143 row_shr:2 row_mask:0xf bank_mask:0xf
	v_fmac_f32_dpp v186, v36, v144 row_shr:2 row_mask:0xf bank_mask:0xf
	v_fmac_f32_dpp v187, v37, v145 row_shr:2 row_mask:0xf bank_mask:0xf
	v_fmac_f32_dpp v180, v46, v158 row_shl:14 row_mask:0xf bank_mask:0xf
	v_fmac_f32_dpp v181, v47, v159 row_shl:14 row_mask:0xf bank_mask:0xf
	v_fmac_f32_dpp v182, v48, v160 row_shl:14 row_mask:0xf bank_mask:0xf
	v_fmac_f32_dpp v183, v49, v161 row_shl:14 row_mask:0xf bank_mask:0xf
	v_fmac_f32_dpp v184, v42, v142 row_shl:14 row_mask:0xf bank_mask:0xf
	v_fmac_f32_dpp v185, v43, v143 row_shl:14 row_mask:0xf bank_mask:0xf
	v_fmac_f32_dpp v186, v44, v144 row_shl:14 row_mask:0xf bank_mask:0xf
	v_fmac_f32_dpp v187, v45, v145 row_shl:14 row_mask:0xf bank_mask:0xf
	v_fmac_f32_dpp v180, v38, v154 row_shr:1 row_mask:0xf bank_mask:0xf
	v_fmac_f32_dpp v181, v39, v155 row_shr:1 row_mask:0xf bank_mask:0xf
	v_fmac_f32_dpp v182, v40, v156 row_shr:1 row_mask:0xf bank_mask:0xf
	v_fmac_f32_dpp v183, v41, v157 row_shr:1 row_mask:0xf bank_mask:0xf
	v_fmac_f32_dpp v184, v34, v138 row_shr:1 row_mask:0xf bank_mask:0xf
	v_fmac_f32_dpp v185, v35, v139 row_shr:1 row_mask:0xf bank_mask:0xf
	v_fmac_f32_dpp v186, v36, v140 row_shr:1 row_mask:0xf bank_mask:0xf
	v_fmac_f32_dpp v187, v37, v141 row_shr:1 row_mask:0xf bank_mask:0xf
	v_fmac_f32_dpp v180, v46, v154 row_shl:15 row_mask:0xf bank_mask:0xf
	v_fmac_f32_dpp v181, v47, v155 row_shl:15 row_mask:0xf bank_mask:0xf
	v_fmac_f32_dpp v182, v48, v156 row_shl:15 row_mask:0xf bank_mask:0xf
	v_fmac_f32_dpp v183, v49, v157 row_shl:15 row_mask:0xf bank_mask:0xf
	v_fmac_f32_dpp v184, v42, v138 row_shl:15 row_mask:0xf bank_mask:0xf
	v_fmac_f32_dpp v185, v43, v139 row_shl:15 row_mask:0xf bank_mask:0xf
	v_fmac_f32_dpp v186, v44, v140 row_shl:15 row_mask:0xf bank_mask:0xf
	v_fmac_f32_dpp v187, v45, v141 row_shl:15 row_mask:0xf bank_mask:0xf
	v_pk_fma_f32 v[180:181], v[38:39], v[150:151], v[180:181]
	v_pk_fma_f32 v[182:183], v[40:41], v[152:153], v[182:183]
	v_pk_fma_f32 v[184:185], v[34:35], v[134:135], v[184:185]
	v_pk_fma_f32 v[186:187], v[36:37], v[136:137], v[186:187]
	v_mul_f32_e32 v188, 0xbfb8aa3b, v180
	v_mul_f32_e32 v189, 0xbfb8aa3b, v181
	v_mul_f32_e32 v190, 0xbfb8aa3b, v182
	v_mul_f32_e32 v191, 0xbfb8aa3b, v183
	v_exp_f32_e32 v188, v188
	v_exp_f32_e32 v189, v189
	v_exp_f32_e32 v190, v190
	v_exp_f32_e32 v191, v191
	v_add_f32_e32 v188, 1.0, v188
	v_add_f32_e32 v189, 1.0, v189
	v_add_f32_e32 v190, 1.0, v190
	v_add_f32_e32 v191, 1.0, v191
	v_rcp_f32_e32 v188, v188
	v_rcp_f32_e32 v189, v189
	v_rcp_f32_e32 v190, v190
	v_rcp_f32_e32 v191, v191
	v_cmp_gt_i32_e32 vcc, 0x3fd0, v230
	v_pk_mul_f32 v[188:189], v[180:181], v[188:189]
	v_pk_mul_f32 v[190:191], v[182:183], v[190:191]
	v_pk_mul_f32 v[188:189], v[184:185], v[188:189]
	v_pk_mul_f32 v[190:191], v[186:187], v[190:191]
	v_add_u32_e32 v234, 0x42000, v233
	v_cvt_pk_bf16_f32 v208, v188, v189
	v_cvt_pk_bf16_f32 v209, v190, v191
	s_and_saveexec_b64 s[4:5], vcc
	s_cbranch_execz .Lupepi_skip11
	global_store_dwordx2 v234, v[208:209], s[26:27] offset:8
; __device__ __forceinline__ void store4(bf16_t* p, f32x4 v) { u32x2 w; w.x = cvt_pk_bf16(v[0], v[1]); w.y = cvt_pk_bf16(v[2], v[3]); *(u32x2*)p = w; }
; __device__ __forceinline__ float dpp_ror1(float x) { float r; asm volatile("s_nop 1\n\tv_mov_b32_dpp %0, %1 row_ror:1 row_mask:0xf bank_mask:0xf" : "=v"(r) : "v"(x)); return r; }
; __device__ __forceinline__ float dpp_ror2(float x) { float r; asm volatile("s_nop 1\n\tv_mov_b32_dpp %0, %1 row_ror:2 row_mask:0xf bank_mask:0xf" : "=v"(r) : "v"(x)); return r; }
;     __device__ __forceinline__ void operator()(const f32x4 (&acc)[2][2][4][2], const Unit& u, int wr, int wc, int fr, int fq) const {
;     ...
;             for (int q = 0; q < 8; ++q) {
;                 const f32x4 ug = acc[q >> 2][0][q & 3][n] * rs[q], uv = acc[q >> 2][1][q & 3][n] * rs[q];
;                 f32x4 res;
; #pragma unroll
;                 for (int j = 0; j < 4; ++j) {
;                     const float ga1 = dpp_ror1(ug[j]), gb1 = dpp_ror1(pg[j]), ga2 = dpp_ror2(ug[j]), gb2 = dpp_ror2(pg[j]);
;                     const float va1 = dpp_ror1(uv[j]), vb1 = dpp_ror1(pv[j]), va2 = dpp_ror2(uv[j]), vb2 = dpp_ror2(pv[j]);
;                     const float g1 = fr >= 1 ? ga1 : gb1, g2 = fr >= 2 ? ga2 : gb2, v1 = fr >= 1 ? va1 : vb1, v2 = fr >= 2 ? va2 : vb2;
;                     const float cgv = bg[j] + wg0[j] * g2 + wg1[j] * g1 + wg2[j] * ug[j];
;                     const float cvv = bv[j] + wv0[j] * v2 + wv1[j] * v1 + wv2[j] * uv[j];
;                     res[j] = cgv * __builtin_amdgcn_rcpf(1.0f + __builtin_amdgcn_exp2f(-1.44269504f * cgv)) * cvv;
;                 }
;                 pg = ug; pv = uv;
;                 const int row = g0 + 16 * q;
;                 if ((q > 0 || fr >= 2) && row < SEQ) store4(ACT + (size_t)row * 2816 + col, res);
.Lupepi_skip11:
	s_or_b64 exec, exec, s[4:5]
	v_pk_mul_f32 v[30:31], v[30:31], v[176:177] op_sel_hi:[1,0]
	v_pk_mul_f32 v[32:33], v[32:33], v[176:177] op_sel_hi:[1,0]
	v_pk_mul_f32 v[26:27], v[26:27], v[176:177] op_sel_hi:[1,0]
	v_pk_mul_f32 v[28:29], v[28:29], v[176:177] op_sel_hi:[1,0]
	v_mov_b32_e32 v180, v146
	v_mov_b32_e32 v181, v147
	v_mov_b32_e32 v182, v148
	v_mov_b32_e32 v183, v149
	v_mov_b32_e32 v184, v130
	v_mov_b32_e32 v185, v131
	v_mov_b32_e32 v186, v132
	v_mov_b32_e32 v187, v133
	v_fmac_f32_dpp v180, v30, v158 row_shr:2 row_mask:0xf bank_mask:0xf
	v_fmac_f32_dpp v181, v31, v159 row_shr:2 row_mask:0xf bank_mask:0xf
	v_fmac_f32_dpp v182, v32, v160 row_shr:2 row_mask:0xf bank_mask:0xf
	v_fmac_f32_dpp v183, v33, v161 row_shr:2 row_mask:0xf bank_mask:0xf
	v_fmac_f32_dpp v184, v26, v142 row_shr:2 row_mask:0xf bank_mask:0xf
	v_fmac_f32_dpp v185, v27, v143 row_shr:2 row_mask:0xf bank_mask:0xf
	v_fmac_f32_dpp v186, v28, v144 row_shr:2 row_mask:0xf bank_mask:0xf
	v_fmac_f32_dpp v187, v29, v145 row_shr:2 row_mask:0xf bank_mask:0xf
	v_fmac_f32_dpp v180, v38, v158 row_shl:14 row_mask:0xf bank_mask:0xf
	v_fmac_f32_dpp v181, v39, v159 row_shl:14 row_mask:0xf bank_mask:0xf
	v_fmac_f32_dpp v182, v40, v160 row_shl:14 row_mask:0xf bank_mask:0xf
	v_fmac_f32_dpp v183, v41, v161 row_shl:14 row_mask:0xf bank_mask:0xf
	v_fmac_f32_dpp v184, v34, v142 row_shl:14 row_mask:0xf bank_mask:0xf
	v_fmac_f32_dpp v185, v35, v143 row_shl:14 row_mask:0xf bank_mask:0xf
	v_fmac_f32_dpp v186, v36, v144 row_shl:14 row_mask:0xf bank_mask:0xf
	v_fmac_f32_dpp v187, v37, v145 row_shl:14 row_mask:0xf bank_mask:0xf
	v_fmac_f32_dpp v180, v30, v154 row_shr:1 row_mask:0xf bank_mask:0xf
	v_fmac_f32_dpp v181, v31, v155 row_shr:1 row_mask:0xf bank_mask:0xf
	v_fmac_f32_dpp v182, v32, v156 row_shr:1 row_mask:0xf bank_mask:0xf
	v_fmac_f32_dpp v183, v33, v157 row_shr:1 row_mask:0xf bank_mask:0xf
	v_fmac_f32_dpp v184, v26, v138 row_shr:1 row_mask:0xf bank_mask:0xf
	v_fmac_f32_dpp v185, v27, v139 row_shr:1 row_mask:0xf bank_mask:0xf
	v_fmac_f32_dpp v186, v28, v140 row_shr:1 row_mask:0xf bank_mask:0xf
	v_fmac_f32_dpp v187, v29, v141 row_shr:1 row_mask:0xf bank_mask:0xf
	v_fmac_f32_dpp v180, v38, v154 row_shl:15 row_mask:0xf bank_mask:0xf
	v_fmac_f32_dpp v181, v39, v155 row_shl:15 row_mask:0xf bank_mask:0xf
	v_fmac_f32_dpp v182, v40, v156 row_shl:15 row_mask:0xf bank_mask:0xf
	v_fmac_f32_dpp v183, v41, v157 row_shl:15 row_mask:0xf bank_mask:0xf
	v_fmac_f32_dpp v184, v34, v138 row_shl:15 row_mask:0xf bank_mask:0xf
	v_fmac_f32_dpp v185, v35, v139 row_shl:15 row_mask:0xf bank_mask:0xf
	v_fmac_f32_dpp v186, v36, v140 row_shl:15 row_mask:0xf bank_mask:0xf
	v_fmac_f32_dpp v187, v37, v141 row_shl:15 row_mask:0xf bank_mask:0xf
	v_pk_fma_f32 v[180:181], v[30:31], v[150:151], v[180:181]
	v_pk_fma_f32 v[182:183], v[32:33], v[152:153], v[182:183]
	v_pk_fma_f32 v[184:185], v[26:27], v[134:135], v[184:185]
	v_pk_fma_f32 v[186:187], v[28:29], v[136:137], v[186:187]
	v_mul_f32_e32 v188, 0xbfb8aa3b, v180
	v_mul_f32_e32 v189, 0xbfb8aa3b, v181
	v_mul_f32_e32 v190, 0xbfb8aa3b, v182
	v_mul_f32_e32 v191, 0xbfb8aa3b, v183
	v_exp_f32_e32 v188, v188
	v_exp_f32_e32 v189, v189
	v_exp_f32_e32 v190, v190
	v_exp_f32_e32 v191, v191
	v_add_f32_e32 v188, 1.0, v188
	v_add_f32_e32 v189, 1.0, v189
	v_add_f32_e32 v190, 1.0, v190
	v_add_f32_e32 v191, 1.0, v191
	v_rcp_f32_e32 v188, v188
	v_rcp_f32_e32 v189, v189
	v_rcp_f32_e32 v190, v190
	v_rcp_f32_e32 v191, v191
	v_cmp_gt_i32_e32 vcc, 0x3fc0, v230
	v_pk_mul_f32 v[188:189], v[180:181], v[188:189]
	v_pk_mul_f32 v[190:191], v[182:183], v[190:191]
	v_pk_mul_f32 v[188:189], v[184:185], v[188:189]
	v_pk_mul_f32 v[190:191], v[186:187], v[190:191]
	v_add_u32_e32 v234, 0x58000, v233
	v_cvt_pk_bf16_f32 v206, v188, v189
	v_cvt_pk_bf16_f32 v207, v190, v191
	s_and_saveexec_b64 s[4:5], vcc
	s_cbranch_execz .Lupepi_skip12
	global_store_dwordx2 v234, v[206:207], s[26:27] offset:8
.Lupepi_skip12:
	s_or_b64 exec, exec, s[4:5]
	v_pk_mul_f32 v[22:23], v[22:23], v[176:177] op_sel:[0,1] op_sel_hi:[1,1]
	v_pk_mul_f32 v[24:25], v[24:25], v[176:177] op_sel:[0,1] op_sel_hi:[1,1]
	v_pk_mul_f32 v[18:19], v[18:19], v[176:177] op_sel:[0,1] op_sel_hi:[1,1]
	v_pk_mul_f32 v[20:21], v[20:21], v[176:177] op_sel:[0,1] op_sel_hi:[1,1]
	v_mov_b32_e32 v180, v146
	v_mov_b32_e32 v181, v147
	v_mov_b32_e32 v182, v148
	v_mov_b32_e32 v183, v149
	v_mov_b32_e32 v184, v130
	v_mov_b32_e32 v185, v131
	v_mov_b32_e32 v186, v132
	v_mov_b32_e32 v187, v133
	v_fmac_f32_dpp v180, v22, v158 row_shr:2 row_mask:0xf bank_mask:0xf
	v_fmac_f32_dpp v181, v23, v159 row_shr:2 row_mask:0xf bank_mask:0xf
	v_fmac_f32_dpp v182, v24, v160 row_shr:2 row_mask:0xf bank_mask:0xf
	v_fmac_f32_dpp v183, v25, v161 row_shr:2 row_mask:0xf bank_mask:0xf
	v_fmac_f32_dpp v184, v18, v142 row_shr:2 row_mask:0xf bank_mask:0xf
	v_fmac_f32_dpp v185, v19, v143 row_shr:2 row_mask:0xf bank_mask:0xf
	v_fmac_f32_dpp v186, v20, v144 row_shr:2 row_mask:0xf bank_mask:0xf
	v_fmac_f32_dpp v187, v21, v145 row_shr:2 row_mask:0xf bank_mask:0xf
	v_fmac_f32_dpp v180, v30, v158 row_shl:14 row_mask:0xf bank_mask:0xf
	v_fmac_f32_dpp v181, v31, v159 row_shl:14 row_mask:0xf bank_mask:0xf
	v_fmac_f32_dpp v182, v32, v160 row_shl:14 row_mask:0xf bank_mask:0xf
	v_fmac_f32_dpp v183, v33, v161 row_shl:14 row_mask:0xf bank_mask:0xf
	v_fmac_f32_dpp v184, v26, v142 row_shl:14 row_mask:0xf bank_mask:0xf
	v_fmac_f32_dpp v185, v27, v143 row_shl:14 row_mask:0xf bank_mask:0xf
	v_fmac_f32_dpp v186, v28, v144 row_shl:14 row_mask:0xf bank_mask:0xf
	v_fmac_f32_dpp v187, v29, v145 row_shl:14 row_mask:0xf bank_mask:0xf
	v_fmac_f32_dpp v180, v22, v154 row_shr:1 row_mask:0xf bank_mask:0xf
; __device__ __forceinline__ void store4(bf16_t* p, f32x4 v) { u32x2 w; w.x = cvt_pk_bf16(v[0], v[1]); w.y = cvt_pk_bf16(v[2], v[3]); *(u32x2*)p = w; }
; __device__ __forceinline__ float dpp_ror1(float x) { float r; asm volatile("s_nop 1\n\tv_mov_b32_dpp %0, %1 row_ror:1 row_mask:0xf bank_mask:0xf" : "=v"(r) : "v"(x)); return r; }
; __device__ __forceinline__ float dpp_ror2(float x) { float r; asm volatile("s_nop 1\n\tv_mov_b32_dpp %0, %1 row_ror:2 row_mask:0xf bank_mask:0xf" : "=v"(r) : "v"(x)); return r; }
;     __device__ __forceinline__ void operator()(const f32x4 (&acc)[2][2][4][2], const Unit& u, int wr, int wc, int fr, int fq) const {
;     ...
;             for (int q = 0; q < 8; ++q) {
;                 const f32x4 ug = acc[q >> 2][0][q & 3][n] * rs[q], uv = acc[q >> 2][1][q & 3][n] * rs[q];
;                 f32x4 res;
; #pragma unroll
;                 for (int j = 0; j < 4; ++j) {
;                     const float ga1 = dpp_ror1(ug[j]), gb1 = dpp_ror1(pg[j]), ga2 = dpp_ror2(ug[j]), gb2 = dpp_ror2(pg[j]);
;                     const float va1 = dpp_ror1(uv[j]), vb1 = dpp_ror1(pv[j]), va2 = dpp_ror2(uv[j]), vb2 = dpp_ror2(pv[j]);
;                     const float g1 = fr >= 1 ? ga1 : gb1, g2 = fr >= 2 ? ga2 : gb2, v1 = fr >= 1 ? va1 : vb1, v2 = fr >= 2 ? va2 : vb2;
;                     const float cgv = bg[j] + wg0[j] * g2 + wg1[j] * g1 + wg2[j] * ug[j];
;                     const float cvv = bv[j] + wv0[j] * v2 + wv1[j] * v1 + wv2[j] * uv[j];
;                     res[j] = cgv * __builtin_amdgcn_rcpf(1.0f + __builtin_amdgcn_exp2f(-1.44269504f * cgv)) * cvv;
;                 }
;                 pg = ug; pv = uv;
;                 const int row = g0 + 16 * q;
;                 if ((q > 0 || fr >= 2) && row < SEQ) store4(ACT + (size_t)row * 2816 + col, res);
	v_fmac_f32_dpp v181, v23, v155 row_shr:1 row_mask:0xf bank_mask:0xf
	v_fmac_f32_dpp v182, v24, v156 row_shr:1 row_mask:0xf bank_mask:0xf
	v_fmac_f32_dpp v183, v25, v157 row_shr:1 row_mask:0xf bank_mask:0xf
	v_fmac_f32_dpp v184, v18, v138 row_shr:1 row_mask:0xf bank_mask:0xf
	v_fmac_f32_dpp v185, v19, v139 row_shr:1 row_mask:0xf bank_mask:0xf
	v_fmac_f32_dpp v186, v20, v140 row_shr:1 row_mask:0xf bank_mask:0xf
	v_fmac_f32_dpp v187, v21, v141 row_shr:1 row_mask:0xf bank_mask:0xf
	v_fmac_f32_dpp v180, v30, v154 row_shl:15 row_mask:0xf bank_mask:0xf
	v_fmac_f32_dpp v181, v31, v155 row_shl:15 row_mask:0xf bank_mask:0xf
	v_fmac_f32_dpp v182, v32, v156 row_shl:15 row_mask:0xf bank_mask:0xf
	v_fmac_f32_dpp v183, v33, v157 row_shl:15 row_mask:0xf bank_mask:0xf
	v_fmac_f32_dpp v184, v26, v138 row_shl:15 row_mask:0xf bank_mask:0xf
	v_fmac_f32_dpp v185, v27, v139 row_shl:15 row_mask:0xf bank_mask:0xf
	v_fmac_f32_dpp v186, v28, v140 row_shl:15 row_mask:0xf bank_mask:0xf
	v_fmac_f32_dpp v187, v29, v141 row_shl:15 row_mask:0xf bank_mask:0xf
	v_pk_fma_f32 v[180:181], v[22:23], v[150:151], v[180:181]
	v_pk_fma_f32 v[182:183], v[24:25], v[152:153], v[182:183]
	v_pk_fma_f32 v[184:185], v[18:19], v[134:135], v[184:185]
	v_pk_fma_f32 v[186:187], v[20:21], v[136:137], v[186:187]
	v_mul_f32_e32 v188, 0xbfb8aa3b, v180
	v_mul_f32_e32 v189, 0xbfb8aa3b, v181
	v_mul_f32_e32 v190, 0xbfb8aa3b, v182
	v_mul_f32_e32 v191, 0xbfb8aa3b, v183
	v_exp_f32_e32 v188, v188
	v_exp_f32_e32 v189, v189
	v_exp_f32_e32 v190, v190
	v_exp_f32_e32 v191, v191
	v_add_f32_e32 v188, 1.0, v188
	v_add_f32_e32 v189, 1.0, v189
	v_add_f32_e32 v190, 1.0, v190
	v_add_f32_e32 v191, 1.0, v191
	v_rcp_f32_e32 v188, v188
	v_rcp_f32_e32 v189, v189
	v_rcp_f32_e32 v190, v190
	v_rcp_f32_e32 v191, v191
	v_cmp_gt_i32_e32 vcc, 0x3fb0, v230
	v_pk_mul_f32 v[188:189], v[180:181], v[188:189]
	v_pk_mul_f32 v[190:191], v[182:183], v[190:191]
	v_pk_mul_f32 v[188:189], v[184:185], v[188:189]
	v_pk_mul_f32 v[190:191], v[186:187], v[190:191]
	v_add_u32_e32 v234, 0x6e000, v233
	v_cvt_pk_bf16_f32 v208, v188, v189
	v_cvt_pk_bf16_f32 v209, v190, v191
	s_and_saveexec_b64 s[4:5], vcc
	s_cbranch_execz .Lupepi_skip13
	global_store_dwordx2 v234, v[208:209], s[26:27] offset:8
.Lupepi_skip13:
	s_or_b64 exec, exec, s[4:5]
	v_pk_mul_f32 v[14:15], v[14:15], v[178:179] op_sel_hi:[1,0]
	v_pk_mul_f32 v[16:17], v[16:17], v[178:179] op_sel_hi:[1,0]
	v_pk_mul_f32 v[10:11], v[10:11], v[178:179] op_sel_hi:[1,0]
	v_pk_mul_f32 v[12:13], v[12:13], v[178:179] op_sel_hi:[1,0]
	v_mov_b32_e32 v180, v146
	v_mov_b32_e32 v181, v147
	v_mov_b32_e32 v182, v148
	v_mov_b32_e32 v183, v149
	v_mov_b32_e32 v184, v130
	v_mov_b32_e32 v185, v131
	v_mov_b32_e32 v186, v132
	v_mov_b32_e32 v187, v133
	v_fmac_f32_dpp v180, v14, v158 row_shr:2 row_mask:0xf bank_mask:0xf
	v_fmac_f32_dpp v181, v15, v159 row_shr:2 row_mask:0xf bank_mask:0xf
	v_fmac_f32_dpp v182, v16, v160 row_shr:2 row_mask:0xf bank_mask:0xf
	v_fmac_f32_dpp v183, v17, v161 row_shr:2 row_mask:0xf bank_mask:0xf
	v_fmac_f32_dpp v184, v10, v142 row_shr:2 row_mask:0xf bank_mask:0xf
	v_fmac_f32_dpp v185, v11, v143 row_shr:2 row_mask:0xf bank_mask:0xf
	v_fmac_f32_dpp v186, v12, v144 row_shr:2 row_mask:0xf bank_mask:0xf
	v_fmac_f32_dpp v187, v13, v145 row_shr:2 row_mask:0xf bank_mask:0xf
	v_fmac_f32_dpp v180, v22, v158 row_shl:14 row_mask:0xf bank_mask:0xf
	v_fmac_f32_dpp v181, v23, v159 row_shl:14 row_mask:0xf bank_mask:0xf
	v_fmac_f32_dpp v182, v24, v160 row_shl:14 row_mask:0xf bank_mask:0xf
	v_fmac_f32_dpp v183, v25, v161 row_shl:14 row_mask:0xf bank_mask:0xf
	v_fmac_f32_dpp v184, v18, v142 row_shl:14 row_mask:0xf bank_mask:0xf
	v_fmac_f32_dpp v185, v19, v143 row_shl:14 row_mask:0xf bank_mask:0xf
	v_fmac_f32_dpp v186, v20, v144 row_shl:14 row_mask:0xf bank_mask:0xf
	v_fmac_f32_dpp v187, v21, v145 row_shl:14 row_mask:0xf bank_mask:0xf
	v_fmac_f32_dpp v180, v14, v154 row_shr:1 row_mask:0xf bank_mask:0xf
	v_fmac_f32_dpp v181, v15, v155 row_shr:1 row_mask:0xf bank_mask:0xf
	v_fmac_f32_dpp v182, v16, v156 row_shr:1 row_mask:0xf bank_mask:0xf
	v_fmac_f32_dpp v183, v17, v157 row_shr:1 row_mask:0xf bank_mask:0xf
	v_fmac_f32_dpp v184, v10, v138 row_shr:1 row_mask:0xf bank_mask:0xf
	v_fmac_f32_dpp v185, v11, v139 row_shr:1 row_mask:0xf bank_mask:0xf
	v_fmac_f32_dpp v186, v12, v140 row_shr:1 row_mask:0xf bank_mask:0xf
	v_fmac_f32_dpp v187, v13, v141 row_shr:1 row_mask:0xf bank_mask:0xf
	v_fmac_f32_dpp v180, v22, v154 row_shl:15 row_mask:0xf bank_mask:0xf
	v_fmac_f32_dpp v181, v23, v155 row_shl:15 row_mask:0xf bank_mask:0xf
	v_fmac_f32_dpp v182, v24, v156 row_shl:15 row_mask:0xf bank_mask:0xf
	v_fmac_f32_dpp v183, v25, v157 row_shl:15 row_mask:0xf bank_mask:0xf
	v_fmac_f32_dpp v184, v18, v138 row_shl:15 row_mask:0xf bank_mask:0xf
	v_fmac_f32_dpp v185, v19, v139 row_shl:15 row_mask:0xf bank_mask:0xf
	v_fmac_f32_dpp v186, v20, v140 row_shl:15 row_mask:0xf bank_mask:0xf
	v_fmac_f32_dpp v187, v21, v141 row_shl:15 row_mask:0xf bank_mask:0xf
	v_pk_fma_f32 v[180:181], v[14:15], v[150:151], v[180:181]
	v_pk_fma_f32 v[182:183], v[16:17], v[152:153], v[182:183]
	v_pk_fma_f32 v[184:185], v[10:11], v[134:135], v[184:185]
	v_pk_fma_f32 v[186:187], v[12:13], v[136:137], v[186:187]
	v_mul_f32_e32 v188, 0xbfb8aa3b, v180
	v_mul_f32_e32 v189, 0xbfb8aa3b, v181
	v_mul_f32_e32 v190, 0xbfb8aa3b, v182
	v_mul_f32_e32 v191, 0xbfb8aa3b, v183
	v_exp_f32_e32 v188, v188
	v_exp_f32_e32 v189, v189
	v_exp_f32_e32 v190, v190
	v_exp_f32_e32 v191, v191
	v_add_f32_e32 v188, 1.0, v188
	v_add_f32_e32 v189, 1.0, v189
	v_add_f32_e32 v190, 1.0, v190
	v_add_f32_e32 v191, 1.0, v191
	v_rcp_f32_e32 v188, v188
	v_rcp_f32_e32 v189, v189
	v_rcp_f32_e32 v190, v190
	v_rcp_f32_e32 v191, v191
	v_cmp_gt_i32_e32 vcc, 0x3fa0, v230
	v_pk_mul_f32 v[188:189], v[180:181], v[188:189]
	v_pk_mul_f32 v[190:191], v[182:183], v[190:191]
	v_pk_mul_f32 v[188:189], v[184:185], v[188:189]
	v_pk_mul_f32 v[190:191], v[186:187], v[190:191]
	v_add_u32_e32 v234, 0x84000, v233
	v_cvt_pk_bf16_f32 v206, v188, v189
	v_cvt_pk_bf16_f32 v207, v190, v191
	s_and_saveexec_b64 s[4:5], vcc
	s_cbranch_execz .Lupepi_skip14
	global_store_dwordx2 v234, v[206:207], s[26:27] offset:8
; __device__ __forceinline__ void store4(bf16_t* p, f32x4 v) { u32x2 w; w.x = cvt_pk_bf16(v[0], v[1]); w.y = cvt_pk_bf16(v[2], v[3]); *(u32x2*)p = w; }
; __device__ __forceinline__ float dpp_ror1(float x) { float r; asm volatile("s_nop 1\n\tv_mov_b32_dpp %0, %1 row_ror:1 row_mask:0xf bank_mask:0xf" : "=v"(r) : "v"(x)); return r; }
; __device__ __forceinline__ float dpp_ror2(float x) { float r; asm volatile("s_nop 1\n\tv_mov_b32_dpp %0, %1 row_ror:2 row_mask:0xf bank_mask:0xf" : "=v"(r) : "v"(x)); return r; }
;     __device__ __forceinline__ void operator()(const f32x4 (&acc)[2][2][4][2], const Unit& u, int wr, int wc, int fr, int fq) const {
;     ...
;             for (int q = 0; q < 8; ++q) {
;                 const f32x4 ug = acc[q >> 2][0][q & 3][n] * rs[q], uv = acc[q >> 2][1][q & 3][n] * rs[q];
;                 f32x4 res;
; #pragma unroll
;                 for (int j = 0; j < 4; ++j) {
;                     const float ga1 = dpp_ror1(ug[j]), gb1 = dpp_ror1(pg[j]), ga2 = dpp_ror2(ug[j]), gb2 = dpp_ror2(pg[j]);
;                     const float va1 = dpp_ror1(uv[j]), vb1 = dpp_ror1(pv[j]), va2 = dpp_ror2(uv[j]), vb2 = dpp_ror2(pv[j]);
;                     const float g1 = fr >= 1 ? ga1 : gb1, g2 = fr >= 2 ? ga2 : gb2, v1 = fr >= 1 ? va1 : vb1, v2 = fr >= 2 ? va2 : vb2;
;                     const float cgv = bg[j] + wg0[j] * g2 + wg1[j] * g1 + wg2[j] * ug[j];
;                     const float cvv = bv[j] + wv0[j] * v2 + wv1[j] * v1 + wv2[j] * uv[j];
;                     res[j] = cgv * __builtin_amdgcn_rcpf(1.0f + __builtin_amdgcn_exp2f(-1.44269504f * cgv)) * cvv;
;                 }
;                 pg = ug; pv = uv;
;                 const int row = g0 + 16 * q;
;                 if ((q > 0 || fr >= 2) && row < SEQ) store4(ACT + (size_t)row * 2816 + col, res);
.Lupepi_skip14:
	s_or_b64 exec, exec, s[4:5]
	v_pk_mul_f32 v[6:7], v[6:7], v[178:179] op_sel:[0,1] op_sel_hi:[1,1]
	v_pk_mul_f32 v[8:9], v[8:9], v[178:179] op_sel:[0,1] op_sel_hi:[1,1]
	v_pk_mul_f32 v[2:3], v[2:3], v[178:179] op_sel:[0,1] op_sel_hi:[1,1]
	v_pk_mul_f32 v[4:5], v[4:5], v[178:179] op_sel:[0,1] op_sel_hi:[1,1]
	v_mov_b32_e32 v180, v146
	v_mov_b32_e32 v181, v147
	v_mov_b32_e32 v182, v148
	v_mov_b32_e32 v183, v149
	v_mov_b32_e32 v184, v130
	v_mov_b32_e32 v185, v131
	v_mov_b32_e32 v186, v132
	v_mov_b32_e32 v187, v133
	v_fmac_f32_dpp v180, v6, v158 row_shr:2 row_mask:0xf bank_mask:0xf
	v_fmac_f32_dpp v181, v7, v159 row_shr:2 row_mask:0xf bank_mask:0xf
	v_fmac_f32_dpp v182, v8, v160 row_shr:2 row_mask:0xf bank_mask:0xf
	v_fmac_f32_dpp v183, v9, v161 row_shr:2 row_mask:0xf bank_mask:0xf
	v_fmac_f32_dpp v184, v2, v142 row_shr:2 row_mask:0xf bank_mask:0xf
	v_fmac_f32_dpp v185, v3, v143 row_shr:2 row_mask:0xf bank_mask:0xf
	v_fmac_f32_dpp v186, v4, v144 row_shr:2 row_mask:0xf bank_mask:0xf
	v_fmac_f32_dpp v187, v5, v145 row_shr:2 row_mask:0xf bank_mask:0xf
	v_fmac_f32_dpp v180, v14, v158 row_shl:14 row_mask:0xf bank_mask:0xf
	v_fmac_f32_dpp v181, v15, v159 row_shl:14 row_mask:0xf bank_mask:0xf
	v_fmac_f32_dpp v182, v16, v160 row_shl:14 row_mask:0xf bank_mask:0xf
	v_fmac_f32_dpp v183, v17, v161 row_shl:14 row_mask:0xf bank_mask:0xf
	v_fmac_f32_dpp v184, v10, v142 row_shl:14 row_mask:0xf bank_mask:0xf
	v_fmac_f32_dpp v185, v11, v143 row_shl:14 row_mask:0xf bank_mask:0xf
	v_fmac_f32_dpp v186, v12, v144 row_shl:14 row_mask:0xf bank_mask:0xf
	v_fmac_f32_dpp v187, v13, v145 row_shl:14 row_mask:0xf bank_mask:0xf
	v_fmac_f32_dpp v180, v6, v154 row_shr:1 row_mask:0xf bank_mask:0xf
	v_fmac_f32_dpp v181, v7, v155 row_shr:1 row_mask:0xf bank_mask:0xf
	v_fmac_f32_dpp v182, v8, v156 row_shr:1 row_mask:0xf bank_mask:0xf
	v_fmac_f32_dpp v183, v9, v157 row_shr:1 row_mask:0xf bank_mask:0xf
	v_fmac_f32_dpp v184, v2, v138 row_shr:1 row_mask:0xf bank_mask:0xf
	v_fmac_f32_dpp v185, v3, v139 row_shr:1 row_mask:0xf bank_mask:0xf
	v_fmac_f32_dpp v186, v4, v140 row_shr:1 row_mask:0xf bank_mask:0xf
	v_fmac_f32_dpp v187, v5, v141 row_shr:1 row_mask:0xf bank_mask:0xf
	v_fmac_f32_dpp v180, v14, v154 row_shl:15 row_mask:0xf bank_mask:0xf
	v_fmac_f32_dpp v181, v15, v155 row_shl:15 row_mask:0xf bank_mask:0xf
	v_fmac_f32_dpp v182, v16, v156 row_shl:15 row_mask:0xf bank_mask:0xf
	v_fmac_f32_dpp v183, v17, v157 row_shl:15 row_mask:0xf bank_mask:0xf
	v_fmac_f32_dpp v184, v10, v138 row_shl:15 row_mask:0xf bank_mask:0xf
	v_fmac_f32_dpp v185, v11, v139 row_shl:15 row_mask:0xf bank_mask:0xf
	v_fmac_f32_dpp v186, v12, v140 row_shl:15 row_mask:0xf bank_mask:0xf
	v_fmac_f32_dpp v187, v13, v141 row_shl:15 row_mask:0xf bank_mask:0xf
	v_pk_fma_f32 v[180:181], v[6:7], v[150:151], v[180:181]
	v_pk_fma_f32 v[182:183], v[8:9], v[152:153], v[182:183]
	v_pk_fma_f32 v[184:185], v[2:3], v[134:135], v[184:185]
	v_pk_fma_f32 v[186:187], v[4:5], v[136:137], v[186:187]
	v_mul_f32_e32 v188, 0xbfb8aa3b, v180
	v_mul_f32_e32 v189, 0xbfb8aa3b, v181
	v_mul_f32_e32 v190, 0xbfb8aa3b, v182
	v_mul_f32_e32 v191, 0xbfb8aa3b, v183
	v_exp_f32_e32 v188, v188
	v_exp_f32_e32 v189, v189
	v_exp_f32_e32 v190, v190
	v_exp_f32_e32 v191, v191
	v_add_f32_e32 v188, 1.0, v188
	v_add_f32_e32 v189, 1.0, v189
	v_add_f32_e32 v190, 1.0, v190
	v_add_f32_e32 v191, 1.0, v191
	v_rcp_f32_e32 v188, v188
	v_rcp_f32_e32 v189, v189
	v_rcp_f32_e32 v190, v190
	v_rcp_f32_e32 v191, v191
	v_cmp_gt_i32_e32 vcc, 0x3f90, v230
	v_pk_mul_f32 v[188:189], v[180:181], v[188:189]
	v_pk_mul_f32 v[190:191], v[182:183], v[190:191]
	v_pk_mul_f32 v[188:189], v[184:185], v[188:189]
	v_pk_mul_f32 v[190:191], v[186:187], v[190:191]
	v_add_u32_e32 v234, 0x9a000, v233
	v_cvt_pk_bf16_f32 v208, v188, v189
	v_cvt_pk_bf16_f32 v209, v190, v191
	s_and_saveexec_b64 s[4:5], vcc
	s_cbranch_execz .LBB0_2355
	global_store_dwordx2 v234, v[208:209], s[26:27] offset:8

; __global__ void __launch_bounds__(512, 2) fwd_kernel(Args args) {
	.amdhsa_kernel _Z10fwd_kernel4Args
		.amdhsa_group_segment_fixed_size 0
		.amdhsa_private_segment_fixed_size 0
		.amdhsa_kernarg_size 432
		.amdhsa_user_sgpr_count 2
		.amdhsa_user_sgpr_dispatch_ptr 0
		.amdhsa_user_sgpr_queue_ptr 0
		.amdhsa_user_sgpr_kernarg_segment_ptr 1
		.amdhsa_user_sgpr_dispatch_id 0
		.amdhsa_user_sgpr_kernarg_preload_length 0
		.amdhsa_user_sgpr_kernarg_preload_offset 0
		.amdhsa_user_sgpr_private_segment_size 0
		.amdhsa_uses_dynamic_stack 0
		.amdhsa_enable_private_segment 0
		.amdhsa_system_sgpr_workgroup_id_x 1
		.amdhsa_system_sgpr_workgroup_id_y 0
		.amdhsa_system_sgpr_workgroup_id_z 0
		.amdhsa_system_sgpr_workgroup_info 0
		.amdhsa_system_vgpr_workitem_id 2
		.amdhsa_next_free_vgpr 256
		.amdhsa_next_free_sgpr 102
		.amdhsa_accum_offset 256
		.amdhsa_reserve_vcc 1
		.amdhsa_float_round_mode_32 0
		.amdhsa_float_round_mode_16_64 0
		.amdhsa_float_denorm_mode_32 3
		.amdhsa_float_denorm_mode_16_64 3
		.amdhsa_dx10_clamp 1
		.amdhsa_ieee_mode 1
		.amdhsa_fp16_overflow 0
		.amdhsa_tg_split 0
		.amdhsa_exception_fp_ieee_invalid_op 0
		.amdhsa_exception_fp_denorm_src 0
		.amdhsa_exception_fp_ieee_div_zero 0
		.amdhsa_exception_fp_ieee_overflow 0
		.amdhsa_exception_fp_ieee_underflow 0
		.amdhsa_exception_fp_ieee_inexact 0
		.amdhsa_exception_int_div_zero 0
	.end_amdhsa_kernel

; __global__ void __launch_bounds__(512, 2) fwd_kernel(Args args) {
amdhsa.kernels:
  - .agpr_count:     0
    .args:
      - .offset:         0
        .size:           176
        .value_kind:     by_value
      - .offset:         176
        .size:           4
        .value_kind:     hidden_block_count_x
      - .offset:         180
        .size:           4
        .value_kind:     hidden_block_count_y
      - .offset:         184
        .size:           4
        .value_kind:     hidden_block_count_z
      - .offset:         188
        .size:           2
        .value_kind:     hidden_group_size_x
      - .offset:         190
        .size:           2
        .value_kind:     hidden_group_size_y
      - .offset:         192
        .size:           2
        .value_kind:     hidden_group_size_z
      - .offset:         194
        .size:           2
        .value_kind:     hidden_remainder_x
      - .offset:         196
        .size:           2
        .value_kind:     hidden_remainder_y
      - .offset:         198
        .size:           2
        .value_kind:     hidden_remainder_z
      - .offset:         216
        .size:           8
        .value_kind:     hidden_global_offset_x
      - .offset:         224
        .size:           8
        .value_kind:     hidden_global_offset_y
      - .offset:         232
        .size:           8
        .value_kind:     hidden_global_offset_z
      - .offset:         240
        .size:           2
        .value_kind:     hidden_grid_dims
      - .offset:         264
        .size:           8
        .value_kind:     hidden_multigrid_sync_arg
      - .offset:         296
        .size:           4
        .value_kind:     hidden_dynamic_lds_size
    .group_segment_fixed_size: 0
    .kernarg_segment_align: 8
    .kernarg_segment_size: 432
    .language:       OpenCL C
    .language_version:
      - 2
      - 0
    .max_flat_workgroup_size: 512
    .name:           _Z10fwd_kernel4Args
    .private_segment_fixed_size: 0
    .sgpr_count:     108
    .sgpr_spill_count: 111
    .symbol:         _Z10fwd_kernel4Args.kd
    .uniform_work_group_size: 1
    .uses_dynamic_stack: false
    .vgpr_count:     256
    .vgpr_spill_count: 0
    .wavefront_size: 64
